# GEMM K-loops unrolled x2 with static LDS buffer parity (immediate +0x8000 offsets, m0 likewise): the four per-iteration base-register toggles removed
# speedup vs baseline: 1.0160x; 1.0007x over previous
.LBB0_143:
	s_lshl_b32 s4, s92, 8
	v_or_b32_e32 v2, s4, v1
	s_lshl_b32 s5, s91, 8
	v_ashrrev_i32_e32 v3, 31, v2
	v_or_b32_e32 v4, s5, v1
	v_lshlrev_b64 v[62:63], 11, v[2:3]
	v_ashrrev_i32_e32 v5, 31, v4
	v_lshl_add_u64 v[2:3], v[134:135], 0, v[62:63]
	v_lshlrev_b64 v[4:5], 11, v[4:5]
	v_lshl_add_u64 v[148:149], v[132:133], 0, v[4:5]
	v_add_co_u32_e32 v4, vcc, 0x20000, v2
	s_mov_b32 s6, 0
	s_nop 0
	v_addc_co_u32_e32 v5, vcc, 0, v3, vcc
	global_load_dwordx4 v[30:33], v[2:3], off
	global_load_dwordx4 v[34:37], v[4:5], off
	v_add_co_u32_e32 v4, vcc, 0x40000, v2
	s_mov_b64 s[0:1], 0
	s_nop 0
	v_addc_co_u32_e32 v5, vcc, 0, v3, vcc
	v_add_co_u32_e32 v2, vcc, 0x60000, v2
	v_lshl_add_u64 v[150:151], v[146:147], 0, v[62:63]
	s_nop 0
	v_addc_co_u32_e32 v3, vcc, 0, v3, vcc
	global_load_dwordx4 v[38:41], v[4:5], off
	global_load_dwordx4 v[42:45], v[2:3], off
	v_add_co_u32_e32 v2, vcc, s43, v148
	s_nop 1
	v_addc_co_u32_e32 v3, vcc, 0, v149, vcc
	s_barrier
	global_load_dwordx4 v[46:49], v[148:149], off
	global_load_dwordx4 v[50:53], v[2:3], off
	v_add_co_u32_e32 v2, vcc, s44, v148
	s_nop 1
	v_addc_co_u32_e32 v3, vcc, 0, v149, vcc
	v_add_co_u32_e32 v4, vcc, 0x60000, v148
	s_nop 1
	v_addc_co_u32_e32 v5, vcc, 0, v149, vcc
	global_load_dwordx4 v[54:57], v[2:3], off
	global_load_dwordx4 v[58:61], v[4:5], off
	v_mov_b32_e32 v2, 0
	v_mov_b32_e32 v3, v2
	v_mov_b32_e32 v4, v2
	v_mov_b32_e32 v5, v2
	v_mov_b32_e32 v6, v2
	v_mov_b32_e32 v7, v2
	v_mov_b32_e32 v8, v2
	v_mov_b32_e32 v9, v2
	v_mov_b32_e32 v10, v2
	v_mov_b32_e32 v11, v2
	v_mov_b32_e32 v12, v2
	v_mov_b32_e32 v13, v2
	v_mov_b32_e32 v14, v2
	v_mov_b32_e32 v15, v2
	v_mov_b32_e32 v16, v2
	v_mov_b32_e32 v17, v2
	v_mov_b32_e32 v18, v2
	v_mov_b32_e32 v19, v2
	v_mov_b32_e32 v20, v2
	v_mov_b32_e32 v21, v2
	v_mov_b32_e32 v22, v2
	v_mov_b32_e32 v23, v2
	v_mov_b32_e32 v24, v2
	v_mov_b32_e32 v25, v2
	v_mov_b32_e32 v26, v2
	v_mov_b32_e32 v27, v2
	v_mov_b32_e32 v28, v2
	v_mov_b32_e32 v29, v2
	v_mov_b32_e32 v62, v2
	v_mov_b32_e32 v63, v2
	v_mov_b32_e32 v64, v2
	v_mov_b32_e32 v65, v2
	v_mov_b32_e32 v66, v2
	v_mov_b32_e32 v67, v2
	v_mov_b32_e32 v68, v2
	v_mov_b32_e32 v69, v2
	v_mov_b32_e32 v70, v2
	v_mov_b32_e32 v71, v2
	v_mov_b32_e32 v72, v2
	v_mov_b32_e32 v73, v2
	v_mov_b32_e32 v74, v2
	v_mov_b32_e32 v75, v2
	v_mov_b32_e32 v76, v2
	v_mov_b32_e32 v77, v2
	v_mov_b32_e32 v78, v2
	v_mov_b32_e32 v79, v2
	v_mov_b32_e32 v80, v2
	v_mov_b32_e32 v81, v2
	v_mov_b32_e32 v82, v2
	v_mov_b32_e32 v83, v2
	s_waitcnt vmcnt(7)
	ds_write_b128 v137, v[30:33]
	s_waitcnt vmcnt(6)
	ds_write_b128 v137, v[34:37] offset:8192
	s_waitcnt vmcnt(5)
	ds_write_b128 v137, v[38:41] offset:16384
	s_waitcnt vmcnt(4)
	ds_write_b128 v137, v[42:45] offset:24576
	s_waitcnt vmcnt(3)
	ds_write_b128 v145, v[46:49]
	s_waitcnt vmcnt(2)
	ds_write_b128 v145, v[50:53] offset:8192
	s_waitcnt vmcnt(1)
	ds_write_b128 v145, v[54:57] offset:16384
	s_waitcnt vmcnt(0)
	ds_write_b128 v145, v[58:61] offset:24576
	v_mov_b32_e32 v30, v2
	v_mov_b32_e32 v31, v2
	v_mov_b32_e32 v32, v2
	v_mov_b32_e32 v33, v2
	v_mov_b32_e32 v34, v2
	v_mov_b32_e32 v35, v2
	v_mov_b32_e32 v36, v2
	v_mov_b32_e32 v37, v2
	v_mov_b32_e32 v38, v2
	v_mov_b32_e32 v39, v2
	v_mov_b32_e32 v40, v2
	v_mov_b32_e32 v41, v2
	v_mov_b32_e32 v42, v2
	v_mov_b32_e32 v43, v2
	v_mov_b32_e32 v44, v2
	v_mov_b32_e32 v45, v2
	v_mov_b32_e32 v46, v2
	v_mov_b32_e32 v47, v2
	v_mov_b32_e32 v48, v2
	v_mov_b32_e32 v49, v2
	v_mov_b32_e32 v50, v2
	v_mov_b32_e32 v51, v2
	v_mov_b32_e32 v52, v2
	v_mov_b32_e32 v53, v2
	v_mov_b32_e32 v54, v2
	v_mov_b32_e32 v55, v2
	v_mov_b32_e32 v56, v2
	v_mov_b32_e32 v57, v2
	v_mov_b32_e32 v58, v2
	v_mov_b32_e32 v59, v2
	v_mov_b32_e32 v60, v2
	v_mov_b32_e32 v61, v2
	v_mov_b32_e32 v84, v2
	v_mov_b32_e32 v85, v2
	v_mov_b32_e32 v86, v2
	v_mov_b32_e32 v87, v2
	v_mov_b32_e32 v88, v2
	v_mov_b32_e32 v89, v2
	v_mov_b32_e32 v90, v2
	v_mov_b32_e32 v91, v2
	v_mov_b32_e32 v92, v2
	v_mov_b32_e32 v93, v2
	v_mov_b32_e32 v94, v2
	v_mov_b32_e32 v95, v2
	v_mov_b32_e32 v96, v2
	v_mov_b32_e32 v97, v2
	v_mov_b32_e32 v98, v2
	v_mov_b32_e32 v99, v2
	v_mov_b32_e32 v100, v2
	v_mov_b32_e32 v101, v2
	v_mov_b32_e32 v102, v2
	v_mov_b32_e32 v103, v2
	v_mov_b32_e32 v104, v2
	v_mov_b32_e32 v105, v2
	v_mov_b32_e32 v106, v2
	v_mov_b32_e32 v107, v2
	v_mov_b32_e32 v108, v2
	v_mov_b32_e32 v109, v2
	v_mov_b32_e32 v110, v2
	v_mov_b32_e32 v111, v2
	v_mov_b32_e32 v112, v2
	v_mov_b32_e32 v113, v2
	v_mov_b32_e32 v114, v2
	v_mov_b32_e32 v115, v2
	v_mov_b32_e32 v116, v2
	v_mov_b32_e32 v117, v2
	v_mov_b32_e32 v118, v2
	v_mov_b32_e32 v119, v2
	v_mov_b32_e32 v120, v2
	v_mov_b32_e32 v121, v2
	v_mov_b32_e32 v122, v2
	v_mov_b32_e32 v123, v2
	v_mov_b32_e32 v124, v2
	v_mov_b32_e32 v125, v2
	v_mov_b32_e32 v126, v2
	v_mov_b32_e32 v127, v2
	v_mov_b32_e32 v128, v2
	v_mov_b32_e32 v129, v2
	s_waitcnt lgkmcnt(0)
	s_barrier
	s_movk_i32 s97, 0x70
	v_readfirstlane_b32 s98, v150
	v_readfirstlane_b32 s99, v151
	v_subrev_u32_e32 v157, s98, v150
	v_bfi_b32 v157, s97, v137, v157
	v_add_u32_e32 v160, s46, v157
	v_add_u32_e32 v161, s47, v157
	v_add_u32_e32 v162, s52, v157
	v_add_u32_e32 v163, s53, v157
	s_add_u32 s98, s98, s0
	s_addc_u32 s99, s99, s1
	s_add_u32 s98, s98, 0x80
	s_addc_u32 s99, s99, 0
	v_readfirstlane_b32 s100, v148
	v_readfirstlane_b32 s101, v149
	v_subrev_u32_e32 v159, s100, v148
	v_bfi_b32 v159, s97, v137, v159
	v_add_u32_e32 v164, 0, v159
	v_add_u32_e32 v165, s43, v159
	v_add_u32_e32 v166, s44, v159
	v_add_u32_e32 v167, s45, v159
	s_add_u32 s100, s100, s0
	s_addc_u32 s101, s101, s1
	s_add_u32 s100, s100, 0x80
	s_addc_u32 s101, s101, 0
	v_readfirstlane_b32 s96, v137
	s_and_b32 s96, s96, 0xfc00
	s_add_u32 m0, s96, 0x8000
	s_nop 0
	global_load_lds_dwordx4 v160, s[98:99]
	s_add_u32 m0, m0, 0x2000
	s_nop 0
	global_load_lds_dwordx4 v161, s[98:99]
	s_add_u32 m0, m0, 0x2000
	s_nop 0
	global_load_lds_dwordx4 v162, s[98:99]
	s_add_u32 m0, m0, 0x2000
	s_nop 0
	global_load_lds_dwordx4 v163, s[98:99]
	s_add_u32 m0, m0, 0xa000
	s_nop 0
	global_load_lds_dwordx4 v164, s[100:101]
	s_add_u32 m0, m0, 0x2000
	s_nop 0
	global_load_lds_dwordx4 v165, s[100:101]
	s_add_u32 m0, m0, 0x2000
	s_nop 0
	global_load_lds_dwordx4 v166, s[100:101]
	s_add_u32 m0, m0, 0x2000
	s_nop 0
	global_load_lds_dwordx4 v167, s[100:101]
	ds_read_b128 v[192:195], v172
	ds_read_b128 v[196:199], v172 offset:2048
	ds_read_b128 v[200:203], v172 offset:4096
	ds_read_b128 v[204:207], v172 offset:6144
	ds_read_b128 v[228:231], v173
	ds_read_b128 v[232:235], v173 offset:2048
	ds_read_b128 v[236:239], v173 offset:4096
	ds_read_b128 v[240:243], v173 offset:6144
.Lg2_p2_loop:
	ds_read_b128 v[208:211], v172 offset:8192
	ds_read_b128 v[212:215], v172 offset:10240
	ds_read_b128 v[218:221], v172 offset:12288
	ds_read_b128 v[224:227], v172 offset:14336
	s_waitcnt lgkmcnt(4)
	v_mfma_f32_16x16x32_bf16 v[126:129], v[228:231], v[192:195], v[126:129]
	v_mfma_f32_16x16x32_bf16 v[122:125], v[232:235], v[192:195], v[122:125]
	v_mfma_f32_16x16x32_bf16 v[118:121], v[236:239], v[192:195], v[118:121]
	v_mfma_f32_16x16x32_bf16 v[114:117], v[240:243], v[192:195], v[114:117]
	v_mfma_f32_16x16x32_bf16 v[110:113], v[228:231], v[196:199], v[110:113]
	v_mfma_f32_16x16x32_bf16 v[106:109], v[232:235], v[196:199], v[106:109]
	v_mfma_f32_16x16x32_bf16 v[102:105], v[236:239], v[196:199], v[102:105]
	v_mfma_f32_16x16x32_bf16 v[98:101], v[240:243], v[196:199], v[98:101]
	v_mfma_f32_16x16x32_bf16 v[94:97], v[228:231], v[200:203], v[94:97]
	v_mfma_f32_16x16x32_bf16 v[90:93], v[232:235], v[200:203], v[90:93]
	v_mfma_f32_16x16x32_bf16 v[86:89], v[236:239], v[200:203], v[86:89]
	v_mfma_f32_16x16x32_bf16 v[82:85], v[240:243], v[200:203], v[82:85]
	v_mfma_f32_16x16x32_bf16 v[78:81], v[228:231], v[204:207], v[78:81]
	v_mfma_f32_16x16x32_bf16 v[74:77], v[232:235], v[204:207], v[74:77]
	v_mfma_f32_16x16x32_bf16 v[70:73], v[236:239], v[204:207], v[70:73]
	v_mfma_f32_16x16x32_bf16 v[66:69], v[240:243], v[204:207], v[66:69]
	ds_read_b128 v[192:195], v216
	ds_read_b128 v[196:199], v216 offset:2048
	ds_read_b128 v[200:203], v216 offset:4096
	ds_read_b128 v[204:207], v216 offset:6144
	ds_read_b128 v[244:247], v217
	ds_read_b128 v[248:251], v217 offset:2048
	ds_read_b128 v[252:255], v217 offset:4096
	ds_read_b128 v[152:155], v217 offset:6144
	s_waitcnt lgkmcnt(8)
	v_mfma_f32_16x16x32_bf16 v[62:65], v[228:231], v[208:211], v[62:65]
	v_mfma_f32_16x16x32_bf16 v[58:61], v[232:235], v[208:211], v[58:61]
	v_mfma_f32_16x16x32_bf16 v[54:57], v[236:239], v[208:211], v[54:57]
	v_mfma_f32_16x16x32_bf16 v[50:53], v[240:243], v[208:211], v[50:53]
	v_mfma_f32_16x16x32_bf16 v[46:49], v[228:231], v[212:215], v[46:49]
	v_mfma_f32_16x16x32_bf16 v[42:45], v[232:235], v[212:215], v[42:45]
	v_mfma_f32_16x16x32_bf16 v[38:41], v[236:239], v[212:215], v[38:41]
	v_mfma_f32_16x16x32_bf16 v[34:37], v[240:243], v[212:215], v[34:37]
	v_mfma_f32_16x16x32_bf16 v[30:33], v[228:231], v[218:221], v[30:33]
	v_mfma_f32_16x16x32_bf16 v[26:29], v[232:235], v[218:221], v[26:29]
	v_mfma_f32_16x16x32_bf16 v[22:25], v[236:239], v[218:221], v[22:25]
	v_mfma_f32_16x16x32_bf16 v[18:21], v[240:243], v[218:221], v[18:21]
	v_mfma_f32_16x16x32_bf16 v[14:17], v[228:231], v[224:227], v[14:17]
	v_mfma_f32_16x16x32_bf16 v[10:13], v[232:235], v[224:227], v[10:13]
	v_mfma_f32_16x16x32_bf16 v[6:9], v[236:239], v[224:227], v[6:9]
	v_mfma_f32_16x16x32_bf16 v[2:5], v[240:243], v[224:227], v[2:5]
	ds_read_b128 v[208:211], v216 offset:8192
	ds_read_b128 v[212:215], v216 offset:10240
	ds_read_b128 v[218:221], v216 offset:12288
	ds_read_b128 v[224:227], v216 offset:14336
	s_waitcnt lgkmcnt(4)
	v_mfma_f32_16x16x32_bf16 v[126:129], v[244:247], v[192:195], v[126:129]
	v_mfma_f32_16x16x32_bf16 v[122:125], v[248:251], v[192:195], v[122:125]
	v_mfma_f32_16x16x32_bf16 v[118:121], v[252:255], v[192:195], v[118:121]
	v_mfma_f32_16x16x32_bf16 v[114:117], v[152:155], v[192:195], v[114:117]
	v_mfma_f32_16x16x32_bf16 v[110:113], v[244:247], v[196:199], v[110:113]
	v_mfma_f32_16x16x32_bf16 v[106:109], v[248:251], v[196:199], v[106:109]
	v_mfma_f32_16x16x32_bf16 v[102:105], v[252:255], v[196:199], v[102:105]
	v_mfma_f32_16x16x32_bf16 v[98:101], v[152:155], v[196:199], v[98:101]
	v_mfma_f32_16x16x32_bf16 v[94:97], v[244:247], v[200:203], v[94:97]
	v_mfma_f32_16x16x32_bf16 v[90:93], v[248:251], v[200:203], v[90:93]
	v_mfma_f32_16x16x32_bf16 v[86:89], v[252:255], v[200:203], v[86:89]
	v_mfma_f32_16x16x32_bf16 v[82:85], v[152:155], v[200:203], v[82:85]
	v_mfma_f32_16x16x32_bf16 v[78:81], v[244:247], v[204:207], v[78:81]
	v_mfma_f32_16x16x32_bf16 v[74:77], v[248:251], v[204:207], v[74:77]
	v_mfma_f32_16x16x32_bf16 v[70:73], v[252:255], v[204:207], v[70:73]
	v_mfma_f32_16x16x32_bf16 v[66:69], v[152:155], v[204:207], v[66:69]
	s_waitcnt vmcnt(0)
	s_waitcnt lgkmcnt(0)
	s_barrier
	s_add_u32 s0, s0, 0x80
	s_addc_u32 s1, s1, 0
	s_add_u32 s98, s98, 0x80
	s_addc_u32 s99, s99, 0
	s_add_u32 s100, s100, 0x80
	s_addc_u32 s101, s101, 0
	s_cmpk_eq_i32 s0, 0x780
	s_cbranch_scc1 .Lg2_p2_tail
	ds_read_b128 v[192:195], v172 offset:32768
	ds_read_b128 v[196:199], v172 offset:34816
	ds_read_b128 v[200:203], v172 offset:36864
	ds_read_b128 v[204:207], v172 offset:38912
	ds_read_b128 v[228:231], v173 offset:32768
	ds_read_b128 v[232:235], v173 offset:34816
	ds_read_b128 v[236:239], v173 offset:36864
	ds_read_b128 v[240:243], v173 offset:38912
	v_mfma_f32_16x16x32_bf16 v[62:65], v[244:247], v[208:211], v[62:65]
	s_mov_b32 m0, s96
	v_mfma_f32_16x16x32_bf16 v[58:61], v[248:251], v[208:211], v[58:61]
	global_load_lds_dwordx4 v160, s[98:99]
	v_mfma_f32_16x16x32_bf16 v[54:57], v[252:255], v[208:211], v[54:57]
	s_add_u32 m0, m0, 0x2000
	v_mfma_f32_16x16x32_bf16 v[50:53], v[152:155], v[208:211], v[50:53]
	global_load_lds_dwordx4 v161, s[98:99]
	v_mfma_f32_16x16x32_bf16 v[46:49], v[244:247], v[212:215], v[46:49]
	s_add_u32 m0, m0, 0x2000
	v_mfma_f32_16x16x32_bf16 v[42:45], v[248:251], v[212:215], v[42:45]
	global_load_lds_dwordx4 v162, s[98:99]
	v_mfma_f32_16x16x32_bf16 v[38:41], v[252:255], v[212:215], v[38:41]
	s_add_u32 m0, m0, 0x2000
	v_mfma_f32_16x16x32_bf16 v[34:37], v[152:155], v[212:215], v[34:37]
	global_load_lds_dwordx4 v163, s[98:99]
	v_mfma_f32_16x16x32_bf16 v[30:33], v[244:247], v[218:221], v[30:33]
	s_add_u32 m0, m0, 0xa000
	v_mfma_f32_16x16x32_bf16 v[26:29], v[248:251], v[218:221], v[26:29]
	global_load_lds_dwordx4 v164, s[100:101]
	v_mfma_f32_16x16x32_bf16 v[22:25], v[252:255], v[218:221], v[22:25]
	s_add_u32 m0, m0, 0x2000
	v_mfma_f32_16x16x32_bf16 v[18:21], v[152:155], v[218:221], v[18:21]
	global_load_lds_dwordx4 v165, s[100:101]
	v_mfma_f32_16x16x32_bf16 v[14:17], v[244:247], v[224:227], v[14:17]
	s_add_u32 m0, m0, 0x2000
	v_mfma_f32_16x16x32_bf16 v[10:13], v[248:251], v[224:227], v[10:13]
	global_load_lds_dwordx4 v166, s[100:101]
	v_mfma_f32_16x16x32_bf16 v[6:9], v[252:255], v[224:227], v[6:9]
	s_add_u32 m0, m0, 0x2000
	v_mfma_f32_16x16x32_bf16 v[2:5], v[152:155], v[224:227], v[2:5]
	global_load_lds_dwordx4 v167, s[100:101]
	ds_read_b128 v[208:211], v172 offset:40960
	ds_read_b128 v[212:215], v172 offset:43008
	ds_read_b128 v[218:221], v172 offset:45056
	ds_read_b128 v[224:227], v172 offset:47104
	s_waitcnt lgkmcnt(4)
	v_mfma_f32_16x16x32_bf16 v[126:129], v[228:231], v[192:195], v[126:129]
	v_mfma_f32_16x16x32_bf16 v[122:125], v[232:235], v[192:195], v[122:125]
	v_mfma_f32_16x16x32_bf16 v[118:121], v[236:239], v[192:195], v[118:121]
	v_mfma_f32_16x16x32_bf16 v[114:117], v[240:243], v[192:195], v[114:117]
	v_mfma_f32_16x16x32_bf16 v[110:113], v[228:231], v[196:199], v[110:113]
	v_mfma_f32_16x16x32_bf16 v[106:109], v[232:235], v[196:199], v[106:109]
	v_mfma_f32_16x16x32_bf16 v[102:105], v[236:239], v[196:199], v[102:105]
	v_mfma_f32_16x16x32_bf16 v[98:101], v[240:243], v[196:199], v[98:101]
	v_mfma_f32_16x16x32_bf16 v[94:97], v[228:231], v[200:203], v[94:97]
	v_mfma_f32_16x16x32_bf16 v[90:93], v[232:235], v[200:203], v[90:93]
	v_mfma_f32_16x16x32_bf16 v[86:89], v[236:239], v[200:203], v[86:89]
	v_mfma_f32_16x16x32_bf16 v[82:85], v[240:243], v[200:203], v[82:85]
	v_mfma_f32_16x16x32_bf16 v[78:81], v[228:231], v[204:207], v[78:81]
	v_mfma_f32_16x16x32_bf16 v[74:77], v[232:235], v[204:207], v[74:77]
	v_mfma_f32_16x16x32_bf16 v[70:73], v[236:239], v[204:207], v[70:73]
	v_mfma_f32_16x16x32_bf16 v[66:69], v[240:243], v[204:207], v[66:69]
	ds_read_b128 v[192:195], v216 offset:32768
	ds_read_b128 v[196:199], v216 offset:34816
	ds_read_b128 v[200:203], v216 offset:36864
	ds_read_b128 v[204:207], v216 offset:38912
	ds_read_b128 v[244:247], v217 offset:32768
	ds_read_b128 v[248:251], v217 offset:34816
	ds_read_b128 v[252:255], v217 offset:36864
	ds_read_b128 v[152:155], v217 offset:38912
	s_waitcnt lgkmcnt(8)
	v_mfma_f32_16x16x32_bf16 v[62:65], v[228:231], v[208:211], v[62:65]
	v_mfma_f32_16x16x32_bf16 v[58:61], v[232:235], v[208:211], v[58:61]
	v_mfma_f32_16x16x32_bf16 v[54:57], v[236:239], v[208:211], v[54:57]
	v_mfma_f32_16x16x32_bf16 v[50:53], v[240:243], v[208:211], v[50:53]
	v_mfma_f32_16x16x32_bf16 v[46:49], v[228:231], v[212:215], v[46:49]
	v_mfma_f32_16x16x32_bf16 v[42:45], v[232:235], v[212:215], v[42:45]
	v_mfma_f32_16x16x32_bf16 v[38:41], v[236:239], v[212:215], v[38:41]
	v_mfma_f32_16x16x32_bf16 v[34:37], v[240:243], v[212:215], v[34:37]
	v_mfma_f32_16x16x32_bf16 v[30:33], v[228:231], v[218:221], v[30:33]
	v_mfma_f32_16x16x32_bf16 v[26:29], v[232:235], v[218:221], v[26:29]
	v_mfma_f32_16x16x32_bf16 v[22:25], v[236:239], v[218:221], v[22:25]
	v_mfma_f32_16x16x32_bf16 v[18:21], v[240:243], v[218:221], v[18:21]
	v_mfma_f32_16x16x32_bf16 v[14:17], v[228:231], v[224:227], v[14:17]
	v_mfma_f32_16x16x32_bf16 v[10:13], v[232:235], v[224:227], v[10:13]
	v_mfma_f32_16x16x32_bf16 v[6:9], v[236:239], v[224:227], v[6:9]
	v_mfma_f32_16x16x32_bf16 v[2:5], v[240:243], v[224:227], v[2:5]
	ds_read_b128 v[208:211], v216 offset:40960
	ds_read_b128 v[212:215], v216 offset:43008
	ds_read_b128 v[218:221], v216 offset:45056
	ds_read_b128 v[224:227], v216 offset:47104
	s_waitcnt lgkmcnt(4)
	v_mfma_f32_16x16x32_bf16 v[126:129], v[244:247], v[192:195], v[126:129]
	v_mfma_f32_16x16x32_bf16 v[122:125], v[248:251], v[192:195], v[122:125]
	v_mfma_f32_16x16x32_bf16 v[118:121], v[252:255], v[192:195], v[118:121]
	v_mfma_f32_16x16x32_bf16 v[114:117], v[152:155], v[192:195], v[114:117]
	v_mfma_f32_16x16x32_bf16 v[110:113], v[244:247], v[196:199], v[110:113]
	v_mfma_f32_16x16x32_bf16 v[106:109], v[248:251], v[196:199], v[106:109]
	v_mfma_f32_16x16x32_bf16 v[102:105], v[252:255], v[196:199], v[102:105]
	v_mfma_f32_16x16x32_bf16 v[98:101], v[152:155], v[196:199], v[98:101]
	v_mfma_f32_16x16x32_bf16 v[94:97], v[244:247], v[200:203], v[94:97]
	v_mfma_f32_16x16x32_bf16 v[90:93], v[248:251], v[200:203], v[90:93]
	v_mfma_f32_16x16x32_bf16 v[86:89], v[252:255], v[200:203], v[86:89]
	v_mfma_f32_16x16x32_bf16 v[82:85], v[152:155], v[200:203], v[82:85]
	v_mfma_f32_16x16x32_bf16 v[78:81], v[244:247], v[204:207], v[78:81]
	v_mfma_f32_16x16x32_bf16 v[74:77], v[248:251], v[204:207], v[74:77]
	v_mfma_f32_16x16x32_bf16 v[70:73], v[252:255], v[204:207], v[70:73]
	v_mfma_f32_16x16x32_bf16 v[66:69], v[152:155], v[204:207], v[66:69]
	s_waitcnt vmcnt(0)
	s_waitcnt lgkmcnt(0)
	s_barrier
	s_add_u32 s0, s0, 0x80
	s_addc_u32 s1, s1, 0
	s_add_u32 s98, s98, 0x80
	s_addc_u32 s99, s99, 0
	s_add_u32 s100, s100, 0x80
	s_addc_u32 s101, s101, 0
	s_cmpk_eq_i32 s0, 0x780
	s_cbranch_scc1 .Lg2_p2_tail
	ds_read_b128 v[192:195], v172
	ds_read_b128 v[196:199], v172 offset:2048
	ds_read_b128 v[200:203], v172 offset:4096
	ds_read_b128 v[204:207], v172 offset:6144
	ds_read_b128 v[228:231], v173
	ds_read_b128 v[232:235], v173 offset:2048
	ds_read_b128 v[236:239], v173 offset:4096
	ds_read_b128 v[240:243], v173 offset:6144
	v_mfma_f32_16x16x32_bf16 v[62:65], v[244:247], v[208:211], v[62:65]
	s_add_u32 m0, s96, 0x8000
	v_mfma_f32_16x16x32_bf16 v[58:61], v[248:251], v[208:211], v[58:61]
	global_load_lds_dwordx4 v160, s[98:99]
	v_mfma_f32_16x16x32_bf16 v[54:57], v[252:255], v[208:211], v[54:57]
	s_add_u32 m0, m0, 0x2000
	v_mfma_f32_16x16x32_bf16 v[50:53], v[152:155], v[208:211], v[50:53]
	global_load_lds_dwordx4 v161, s[98:99]
	v_mfma_f32_16x16x32_bf16 v[46:49], v[244:247], v[212:215], v[46:49]
	s_add_u32 m0, m0, 0x2000
	v_mfma_f32_16x16x32_bf16 v[42:45], v[248:251], v[212:215], v[42:45]
	global_load_lds_dwordx4 v162, s[98:99]
	v_mfma_f32_16x16x32_bf16 v[38:41], v[252:255], v[212:215], v[38:41]
	s_add_u32 m0, m0, 0x2000
	v_mfma_f32_16x16x32_bf16 v[34:37], v[152:155], v[212:215], v[34:37]
	global_load_lds_dwordx4 v163, s[98:99]
	v_mfma_f32_16x16x32_bf16 v[30:33], v[244:247], v[218:221], v[30:33]
	s_add_u32 m0, m0, 0xa000
	v_mfma_f32_16x16x32_bf16 v[26:29], v[248:251], v[218:221], v[26:29]
	global_load_lds_dwordx4 v164, s[100:101]
	v_mfma_f32_16x16x32_bf16 v[22:25], v[252:255], v[218:221], v[22:25]
	s_add_u32 m0, m0, 0x2000
	v_mfma_f32_16x16x32_bf16 v[18:21], v[152:155], v[218:221], v[18:21]
	global_load_lds_dwordx4 v165, s[100:101]
	v_mfma_f32_16x16x32_bf16 v[14:17], v[244:247], v[224:227], v[14:17]
	s_add_u32 m0, m0, 0x2000
	v_mfma_f32_16x16x32_bf16 v[10:13], v[248:251], v[224:227], v[10:13]
	global_load_lds_dwordx4 v166, s[100:101]
	v_mfma_f32_16x16x32_bf16 v[6:9], v[252:255], v[224:227], v[6:9]
	s_add_u32 m0, m0, 0x2000
	v_mfma_f32_16x16x32_bf16 v[2:5], v[152:155], v[224:227], v[2:5]
	global_load_lds_dwordx4 v167, s[100:101]
	s_branch .Lg2_p2_loop
.Lg2_p2_tail:
	v_mfma_f32_16x16x32_bf16 v[62:65], v[244:247], v[208:211], v[62:65]
	v_mfma_f32_16x16x32_bf16 v[58:61], v[248:251], v[208:211], v[58:61]
	v_mfma_f32_16x16x32_bf16 v[54:57], v[252:255], v[208:211], v[54:57]
	v_mfma_f32_16x16x32_bf16 v[50:53], v[152:155], v[208:211], v[50:53]
	v_mfma_f32_16x16x32_bf16 v[46:49], v[244:247], v[212:215], v[46:49]
	v_mfma_f32_16x16x32_bf16 v[42:45], v[248:251], v[212:215], v[42:45]
	v_mfma_f32_16x16x32_bf16 v[38:41], v[252:255], v[212:215], v[38:41]
	v_mfma_f32_16x16x32_bf16 v[34:37], v[152:155], v[212:215], v[34:37]
	v_mfma_f32_16x16x32_bf16 v[30:33], v[244:247], v[218:221], v[30:33]
	v_mfma_f32_16x16x32_bf16 v[26:29], v[248:251], v[218:221], v[26:29]
	v_mfma_f32_16x16x32_bf16 v[22:25], v[252:255], v[218:221], v[22:25]
	v_mfma_f32_16x16x32_bf16 v[18:21], v[152:155], v[218:221], v[18:21]
	v_mfma_f32_16x16x32_bf16 v[14:17], v[244:247], v[224:227], v[14:17]
	v_mfma_f32_16x16x32_bf16 v[10:13], v[248:251], v[224:227], v[10:13]
	v_mfma_f32_16x16x32_bf16 v[6:9], v[252:255], v[224:227], v[6:9]
	v_mfma_f32_16x16x32_bf16 v[2:5], v[152:155], v[224:227], v[2:5]
	ds_read_b128 v[148:151], v173 offset:32768
	ds_read_b128 v[152:155], v173 offset:34816
	ds_read_b128 v[156:159], v173 offset:36864
	ds_read_b128 v[160:163], v173 offset:38912
	ds_read_b128 v[164:167], v172 offset:32768
	ds_read_b128 v[168:171], v172 offset:34816
	ds_read_b128 v[180:183], v172 offset:36864
	ds_read_b128 v[184:187], v172 offset:38912
	s_setprio 1
	s_waitcnt lgkmcnt(3)
	v_mfma_f32_16x16x32_bf16 v[126:129], v[148:151], v[164:167], v[126:129]
	v_mfma_f32_16x16x32_bf16 v[122:125], v[152:155], v[164:167], v[122:125]
	v_mfma_f32_16x16x32_bf16 v[118:121], v[156:159], v[164:167], v[118:121]
	v_mfma_f32_16x16x32_bf16 v[114:117], v[160:163], v[164:167], v[114:117]
	s_waitcnt lgkmcnt(2)
	v_mfma_f32_16x16x32_bf16 v[110:113], v[148:151], v[168:171], v[110:113]
	v_mfma_f32_16x16x32_bf16 v[106:109], v[152:155], v[168:171], v[106:109]
	v_mfma_f32_16x16x32_bf16 v[102:105], v[156:159], v[168:171], v[102:105]
	v_mfma_f32_16x16x32_bf16 v[98:101], v[160:163], v[168:171], v[98:101]
	s_waitcnt lgkmcnt(1)
	v_mfma_f32_16x16x32_bf16 v[94:97], v[148:151], v[180:183], v[94:97]
	v_mfma_f32_16x16x32_bf16 v[90:93], v[152:155], v[180:183], v[90:93]
	v_mfma_f32_16x16x32_bf16 v[86:89], v[156:159], v[180:183], v[86:89]
	v_mfma_f32_16x16x32_bf16 v[82:85], v[160:163], v[180:183], v[82:85]
	s_waitcnt lgkmcnt(0)
	v_mfma_f32_16x16x32_bf16 v[78:81], v[148:151], v[184:187], v[78:81]
	v_mfma_f32_16x16x32_bf16 v[74:77], v[152:155], v[184:187], v[74:77]
	v_mfma_f32_16x16x32_bf16 v[70:73], v[156:159], v[184:187], v[70:73]
	v_mfma_f32_16x16x32_bf16 v[66:69], v[160:163], v[184:187], v[66:69]
	s_setprio 0
	ds_read_b128 v[164:167], v172 offset:40960
	ds_read_b128 v[168:171], v172 offset:43008
	ds_read_b128 v[180:183], v172 offset:45056
	ds_read_b128 v[184:187], v172 offset:47104
	s_setprio 1
	s_waitcnt lgkmcnt(3)
	v_mfma_f32_16x16x32_bf16 v[62:65], v[148:151], v[164:167], v[62:65]
	v_mfma_f32_16x16x32_bf16 v[58:61], v[152:155], v[164:167], v[58:61]
	v_mfma_f32_16x16x32_bf16 v[54:57], v[156:159], v[164:167], v[54:57]
	v_mfma_f32_16x16x32_bf16 v[50:53], v[160:163], v[164:167], v[50:53]
	s_waitcnt lgkmcnt(2)
	v_mfma_f32_16x16x32_bf16 v[46:49], v[148:151], v[168:171], v[46:49]
	v_mfma_f32_16x16x32_bf16 v[42:45], v[152:155], v[168:171], v[42:45]
	v_mfma_f32_16x16x32_bf16 v[38:41], v[156:159], v[168:171], v[38:41]
	v_mfma_f32_16x16x32_bf16 v[34:37], v[160:163], v[168:171], v[34:37]
	s_waitcnt lgkmcnt(1)
	v_mfma_f32_16x16x32_bf16 v[30:33], v[148:151], v[180:183], v[30:33]
	v_mfma_f32_16x16x32_bf16 v[26:29], v[152:155], v[180:183], v[26:29]
	v_mfma_f32_16x16x32_bf16 v[22:25], v[156:159], v[180:183], v[22:25]
	v_mfma_f32_16x16x32_bf16 v[18:21], v[160:163], v[180:183], v[18:21]
	s_waitcnt lgkmcnt(0)
	v_mfma_f32_16x16x32_bf16 v[148:151], v[148:151], v[184:187], v[14:17]
	v_mfma_f32_16x16x32_bf16 v[152:155], v[152:155], v[184:187], v[10:13]
	v_mfma_f32_16x16x32_bf16 v[156:159], v[156:159], v[184:187], v[6:9]
	v_mfma_f32_16x16x32_bf16 v[160:163], v[160:163], v[184:187], v[2:5]
	s_setprio 0
	ds_read_b128 v[164:167], v217 offset:32768
	ds_read_b128 v[168:171], v217 offset:34816
	ds_read_b128 v[180:183], v217 offset:36864
	ds_read_b128 v[184:187], v217 offset:38912
	ds_read_b128 v[2:5], v216 offset:32768
	ds_read_b128 v[188:191], v216 offset:34816
	ds_read_b128 v[192:195], v216 offset:36864
	ds_read_b128 v[196:199], v216 offset:38912
	s_setprio 1
	s_waitcnt lgkmcnt(3)
	v_mfma_f32_16x16x32_bf16 v[14:17], v[164:167], v[2:5], v[126:129]
	v_mfma_f32_16x16x32_bf16 v[10:13], v[168:171], v[2:5], v[122:125]
	v_mfma_f32_16x16x32_bf16 v[6:9], v[180:183], v[2:5], v[118:121]
	v_mfma_f32_16x16x32_bf16 v[2:5], v[184:187], v[2:5], v[114:117]
	s_waitcnt lgkmcnt(2)
	v_mfma_f32_16x16x32_bf16 v[126:129], v[164:167], v[188:191], v[110:113]
	v_mfma_f32_16x16x32_bf16 v[122:125], v[168:171], v[188:191], v[106:109]
	v_mfma_f32_16x16x32_bf16 v[118:121], v[180:183], v[188:191], v[102:105]
	v_mfma_f32_16x16x32_bf16 v[114:117], v[184:187], v[188:191], v[98:101]
	s_waitcnt lgkmcnt(1)
	v_mfma_f32_16x16x32_bf16 v[110:113], v[164:167], v[192:195], v[94:97]
	v_mfma_f32_16x16x32_bf16 v[106:109], v[168:171], v[192:195], v[90:93]
	v_mfma_f32_16x16x32_bf16 v[102:105], v[180:183], v[192:195], v[86:89]
	v_mfma_f32_16x16x32_bf16 v[98:101], v[184:187], v[192:195], v[82:85]
	s_waitcnt lgkmcnt(0)
	v_mfma_f32_16x16x32_bf16 v[94:97], v[164:167], v[196:199], v[78:81]
	v_mfma_f32_16x16x32_bf16 v[90:93], v[168:171], v[196:199], v[74:77]
	v_mfma_f32_16x16x32_bf16 v[86:89], v[180:183], v[196:199], v[70:73]
	v_mfma_f32_16x16x32_bf16 v[82:85], v[184:187], v[196:199], v[66:69]
	s_setprio 0
	s_nop 1
	ds_read_b128 v[66:69], v216 offset:40960
	ds_read_b128 v[188:191], v216 offset:43008
	ds_read_b128 v[192:195], v216 offset:45056
	ds_read_b128 v[196:199], v216 offset:47104
	s_setprio 1
	s_waitcnt lgkmcnt(3)
	v_mfma_f32_16x16x32_bf16 v[78:81], v[164:167], v[66:69], v[62:65]
	v_mfma_f32_16x16x32_bf16 v[74:77], v[168:171], v[66:69], v[58:61]
	v_mfma_f32_16x16x32_bf16 v[70:73], v[180:183], v[66:69], v[54:57]
	v_mfma_f32_16x16x32_bf16 v[66:69], v[184:187], v[66:69], v[50:53]
	s_waitcnt lgkmcnt(2)
	v_mfma_f32_16x16x32_bf16 v[62:65], v[164:167], v[188:191], v[46:49]
	v_mfma_f32_16x16x32_bf16 v[58:61], v[168:171], v[188:191], v[42:45]
	v_mfma_f32_16x16x32_bf16 v[54:57], v[180:183], v[188:191], v[38:41]
	v_mfma_f32_16x16x32_bf16 v[50:53], v[184:187], v[188:191], v[34:37]
	s_waitcnt lgkmcnt(1)
	v_mfma_f32_16x16x32_bf16 v[46:49], v[164:167], v[192:195], v[30:33]
	v_mfma_f32_16x16x32_bf16 v[42:45], v[168:171], v[192:195], v[26:29]
	v_mfma_f32_16x16x32_bf16 v[38:41], v[180:183], v[192:195], v[22:25]
	v_mfma_f32_16x16x32_bf16 v[34:37], v[184:187], v[192:195], v[18:21]
	s_waitcnt lgkmcnt(0)
	v_mfma_f32_16x16x32_bf16 v[30:33], v[164:167], v[196:199], v[148:151]
	v_mfma_f32_16x16x32_bf16 v[26:29], v[168:171], v[196:199], v[152:155]
	v_mfma_f32_16x16x32_bf16 v[22:25], v[180:183], v[196:199], v[156:159]
	v_mfma_f32_16x16x32_bf16 v[18:21], v[184:187], v[196:199], v[160:163]
	s_setprio 0
	v_add_u32_e32 v179, s4, v174
	v_or_b32_e32 v130, s5, v175
	v_ashrrev_i32_e32 v149, 31, v130
	v_mov_b32_e32 v148, v130
	v_or_b32_e32 v154, v179, v176
	v_cmp_gt_i32_e64 s[4:5], s56, v130
	v_cmp_gt_i32_e64 s[6:7], s57, v130
	v_cmp_lt_i32_e64 s[0:1], s58, v130
	v_lshl_add_u64 v[150:151], v[130:131], 1, s[10:11]
	v_lshl_add_u64 v[148:149], v[148:149], 1, v[142:143]
	v_lshlrev_b32_e32 v152, 2, v136
	v_mul_hi_i32 v155, v154, s62
	s_barrier
	s_and_saveexec_b64 s[28:29], s[4:5]
	s_xor_b64 s[28:29], exec, s[28:29]
	s_cbranch_execz .LBB0_171
	v_mov_b32_e32 v153, s79
	v_mov_b32_e32 v156, s77
	v_cndmask_b32_e64 v157, v153, v156, s[6:7]
	v_mov_b32_e32 v153, s78
	v_mov_b32_e32 v156, s76
	v_cndmask_b32_e64 v156, v153, v156, s[6:7]
	v_mov_b32_e32 v153, v131
	v_lshl_add_u64 v[156:157], v[156:157], 0, v[152:153]
	global_load_dwordx4 v[158:161], v[156:157], off
	global_load_dwordx4 v[164:167], v[156:157], off offset:64
	global_load_dwordx4 v[182:185], v[156:157], off offset:128
	global_load_dwordx4 v[186:189], v[156:157], off offset:192
	v_mul_f32_e32 v191, v15, v15
	v_fmac_f32_e32 v191, v14, v14
	v_fmac_f32_e32 v191, v16, v16
	v_fmac_f32_e32 v191, v17, v17
	v_fmac_f32_e32 v191, v10, v10
	v_fmac_f32_e32 v191, v11, v11
	v_fmac_f32_e32 v191, v12, v12
	v_pk_mul_f32 v[168:169], v[6:7], v[6:7]
	v_fmac_f32_e32 v191, v13, v13
	v_add_f32_e32 v168, v168, v191
	v_pk_mul_f32 v[162:163], v[8:9], v[8:9]
	v_add_f32_e32 v168, v169, v168
	v_add_f32_e32 v162, v162, v168
	v_and_b32_e32 v190, 64, v178
	v_pk_mul_f32 v[180:181], v[2:3], v[2:3]
	v_add_f32_e32 v162, v163, v162
	v_xor_b32_e32 v153, 16, v178
	v_add_u32_e32 v190, 64, v190
	v_add_f32_e32 v162, v180, v162
	v_pk_mul_f32 v[170:171], v[4:5], v[4:5]
	v_cmp_lt_i32_e32 vcc, v153, v190
	v_add_f32_e32 v162, v181, v162
	v_add_f32_e32 v162, v170, v162
	v_cndmask_b32_e32 v153, v178, v153, vcc
	v_lshlrev_b32_e32 v153, 2, v153
	v_add_f32_e32 v162, v171, v162
	ds_bpermute_b32 v163, v153, v162
	v_xor_b32_e32 v168, 32, v178
	v_cmp_lt_i32_e32 vcc, v168, v190
	s_waitcnt lgkmcnt(0)
	v_add_f32_e32 v162, v162, v163
	v_cndmask_b32_e32 v168, v178, v168, vcc
	v_lshlrev_b32_e32 v180, 2, v168
	ds_bpermute_b32 v163, v180, v162
	v_lshrrev_b32_e32 v168, 31, v155
	v_ashrrev_i32_e32 v155, 11, v155
	v_add_u32_e32 v155, v155, v168
	v_mul_i32_i24_e32 v155, 0x2100, v155
	s_waitcnt lgkmcnt(0)
	v_add_f32_e32 v162, v162, v163
	v_fmamk_f32 v162, v162, 0x3c800000, v177
	v_mul_f32_e32 v163, 0x4b800000, v162
	v_cmp_gt_f32_e32 vcc, s59, v162
	v_sub_u32_e32 v155, v154, v155
	s_nop 0
	v_cndmask_b32_e32 v162, v162, v163, vcc
	v_rsq_f32_e32 v162, v162
	s_nop 0
	v_mul_f32_e32 v163, 0x45800000, v162
	v_cndmask_b32_e32 v162, v162, v163, vcc
	v_pk_mul_f32 v[14:15], v[14:15], v[162:163] op_sel_hi:[1,0]
	v_pk_mul_f32 v[16:17], v[16:17], v[162:163] op_sel_hi:[1,0]
	v_pk_mul_f32 v[10:11], v[10:11], v[162:163] op_sel_hi:[1,0]
	v_pk_mul_f32 v[12:13], v[12:13], v[162:163] op_sel_hi:[1,0]
	v_pk_mul_f32 v[6:7], v[6:7], v[162:163] op_sel_hi:[1,0]
	v_pk_mul_f32 v[8:9], v[8:9], v[162:163] op_sel_hi:[1,0]
	v_pk_mul_f32 v[170:171], v[2:3], v[162:163] op_sel_hi:[1,0]
	v_pk_mul_f32 v[4:5], v[4:5], v[162:163] op_sel_hi:[1,0]
	v_cmp_lt_i32_e32 vcc, s63, v155
	s_waitcnt vmcnt(3)
	v_pk_mul_f32 v[168:169], v[160:161], v[16:17]
	v_pk_mul_f32 v[2:3], v[158:159], v[14:15]
	s_waitcnt vmcnt(2)
	v_pk_mul_f32 v[162:163], v[166:167], v[12:13]
	v_pk_mul_f32 v[160:161], v[164:165], v[10:11]
	s_waitcnt vmcnt(1)
	v_pk_mul_f32 v[166:167], v[184:185], v[8:9]
	v_pk_mul_f32 v[164:165], v[182:183], v[6:7]
	s_waitcnt vmcnt(0)
	v_pk_mul_f32 v[158:159], v[188:189], v[4:5]
	v_pk_mul_f32 v[4:5], v[186:187], v[170:171]
	s_and_saveexec_b64 s[38:39], vcc
	s_cbranch_execz .LBB0_148
	v_add_u32_e32 v6, 0xffffff00, v155
	v_lshlrev_b32_e32 v10, 6, v155
	v_and_b32_e32 v14, 0xffffffc0, v6
	v_mov_b32_e32 v15, v131
	v_and_b32_e32 v170, 0x3c0, v10
	v_mov_b32_e32 v171, v131
	v_lshl_add_u64 v[6:7], v[140:141], 0, v[14:15]
	v_lshl_add_u64 v[10:11], v[140:141], 0, v[170:171]
	global_load_dwordx4 v[6:9], v[6:7], off
	v_lshl_add_u64 v[14:15], v[138:139], 0, v[14:15]
	global_load_dwordx4 v[10:13], v[10:11], off
	v_lshl_add_u64 v[170:171], v[138:139], 0, v[170:171]
	global_load_dwordx4 v[14:17], v[14:15], off
	s_waitcnt vmcnt(2)
	v_pk_mul_f32 v[186:187], v[160:161], v[6:7]
	global_load_dwordx4 v[182:185], v[170:171], off
	v_pk_mul_f32 v[170:171], v[162:163], v[8:9]
	v_pk_mul_f32 v[8:9], v[168:169], v[8:9]
	v_pk_mul_f32 v[6:7], v[2:3], v[6:7]
	s_waitcnt vmcnt(2)
	v_pk_mul_f32 v[188:189], v[158:159], v[12:13]
	v_pk_mul_f32 v[190:191], v[4:5], v[10:11]
	v_pk_mul_f32 v[12:13], v[166:167], v[12:13]
	v_pk_mul_f32 v[10:11], v[164:165], v[10:11]
	s_waitcnt vmcnt(1)
	v_pk_fma_f32 v[168:169], v[168:169], v[16:17], v[170:171] neg_lo:[0,0,1] neg_hi:[0,0,1]
	v_pk_fma_f32 v[2:3], v[2:3], v[14:15], v[186:187] neg_lo:[0,0,1] neg_hi:[0,0,1]
	v_pk_fma_f32 v[162:163], v[162:163], v[16:17], v[8:9]
	v_pk_fma_f32 v[160:161], v[160:161], v[14:15], v[6:7]
	s_waitcnt vmcnt(0)
	v_pk_fma_f32 v[166:167], v[166:167], v[184:185], v[188:189] neg_lo:[0,0,1] neg_hi:[0,0,1]
	v_pk_fma_f32 v[164:165], v[164:165], v[182:183], v[190:191] neg_lo:[0,0,1] neg_hi:[0,0,1]
	v_pk_fma_f32 v[158:159], v[158:159], v[184:185], v[12:13]
	v_pk_fma_f32 v[4:5], v[4:5], v[182:183], v[10:11]

.LBB0_248:
	s_lshl_b32 s56, s52, 8
	v_or_b32_e32 v2, s56, v1
	v_ashrrev_i32_e32 v3, 31, v2
	v_lshlrev_b64 v[62:63], 11, v[2:3]
	v_lshl_add_u64 v[2:3], v[130:131], 0, v[62:63]
	v_add_co_u32_e32 v6, vcc, 0x20000, v2
	s_lshl_b32 s53, s47, 8
	s_nop 0
	v_addc_co_u32_e32 v7, vcc, 0, v3, vcc
	v_or_b32_e32 v4, s53, v1
	global_load_dwordx4 v[30:33], v[2:3], off
	global_load_dwordx4 v[34:37], v[6:7], off
	v_add_co_u32_e32 v6, vcc, 0x40000, v2
	v_ashrrev_i32_e32 v5, 31, v4
	s_nop 0
	v_addc_co_u32_e32 v7, vcc, 0, v3, vcc
	v_lshlrev_b64 v[64:65], 11, v[4:5]
	v_add_co_u32_e32 v2, vcc, 0x60000, v2
	v_lshl_add_u64 v[4:5], v[132:133], 0, v[64:65]
	s_nop 0
	v_addc_co_u32_e32 v3, vcc, 0, v3, vcc
	global_load_dwordx4 v[38:41], v[6:7], off
	global_load_dwordx4 v[42:45], v[2:3], off
	v_add_co_u32_e32 v2, vcc, s12, v4
	s_waitcnt vmcnt(63) expcnt(7) lgkmcnt(15)
	s_nop 0
	v_addc_co_u32_e32 v3, vcc, 0, v5, vcc
	s_barrier
	global_load_dwordx4 v[46:49], v[4:5], off
	global_load_dwordx4 v[50:53], v[2:3], off
	v_add_co_u32_e32 v2, vcc, s13, v4
	s_mov_b32 s57, 0
	s_nop 0
	v_addc_co_u32_e32 v3, vcc, 0, v5, vcc
	v_add_co_u32_e32 v4, vcc, s14, v4
	s_mov_b64 s[8:9], 0
	s_nop 0
	v_addc_co_u32_e32 v5, vcc, 0, v5, vcc
	global_load_dwordx4 v[54:57], v[2:3], off
	global_load_dwordx4 v[58:61], v[4:5], off
	v_mov_b32_e32 v2, 0
	v_mov_b32_e32 v3, v2
	v_mov_b32_e32 v4, v2
	v_mov_b32_e32 v5, v2
	v_mov_b32_e32 v6, v2
	v_mov_b32_e32 v7, v2
	v_mov_b32_e32 v8, v2
	v_mov_b32_e32 v9, v2
	v_mov_b32_e32 v10, v2
	v_mov_b32_e32 v11, v2
	v_mov_b32_e32 v12, v2
	v_mov_b32_e32 v13, v2
	v_mov_b32_e32 v14, v2
	v_mov_b32_e32 v15, v2
	v_mov_b32_e32 v16, v2
	v_mov_b32_e32 v17, v2
	v_mov_b32_e32 v18, v2
	v_mov_b32_e32 v19, v2
	v_mov_b32_e32 v20, v2
	v_mov_b32_e32 v21, v2
	v_mov_b32_e32 v22, v2
	v_mov_b32_e32 v23, v2
	v_mov_b32_e32 v24, v2
	v_mov_b32_e32 v25, v2
	v_mov_b32_e32 v26, v2
	v_mov_b32_e32 v27, v2
	v_mov_b32_e32 v28, v2
	v_lshl_add_u64 v[136:137], v[134:135], 0, v[62:63]
	v_lshl_add_u64 v[138:139], v[134:135], 0, v[64:65]
	v_mov_b32_e32 v29, v2
	v_mov_b32_e32 v62, v2
	v_mov_b32_e32 v63, v2
	v_mov_b32_e32 v64, v2
	v_mov_b32_e32 v65, v2
	v_mov_b32_e32 v66, v2
	v_mov_b32_e32 v67, v2
	v_mov_b32_e32 v68, v2
	v_mov_b32_e32 v69, v2
	v_mov_b32_e32 v70, v2
	v_mov_b32_e32 v71, v2
	v_mov_b32_e32 v72, v2
	v_mov_b32_e32 v73, v2
	v_mov_b32_e32 v74, v2
	v_mov_b32_e32 v75, v2
	v_mov_b32_e32 v76, v2
	v_mov_b32_e32 v77, v2
	v_mov_b32_e32 v78, v2
	v_mov_b32_e32 v79, v2
	v_mov_b32_e32 v80, v2
	v_mov_b32_e32 v81, v2
	v_mov_b32_e32 v82, v2
	v_mov_b32_e32 v83, v2
	v_mov_b32_e32 v84, v2
	s_waitcnt vmcnt(7)
	ds_write_b128 v146, v[30:33]
	s_waitcnt vmcnt(6)
	ds_write_b128 v146, v[34:37] offset:8192
	s_waitcnt vmcnt(5)
	ds_write_b128 v146, v[38:41] offset:16384
	s_waitcnt vmcnt(4)
	ds_write_b128 v146, v[42:45] offset:24576
	s_waitcnt vmcnt(3)
	ds_write_b128 v147, v[46:49]
	s_waitcnt vmcnt(2)
	ds_write_b128 v147, v[50:53] offset:8192
	s_waitcnt vmcnt(1)
	ds_write_b128 v147, v[54:57] offset:16384
	s_waitcnt vmcnt(0)
	ds_write_b128 v147, v[58:61] offset:24576
	v_mov_b32_e32 v30, v2
	v_mov_b32_e32 v31, v2
	v_mov_b32_e32 v32, v2
	v_mov_b32_e32 v33, v2
	v_mov_b32_e32 v34, v2
	v_mov_b32_e32 v35, v2
	v_mov_b32_e32 v36, v2
	v_mov_b32_e32 v37, v2
	v_mov_b32_e32 v38, v2
	v_mov_b32_e32 v39, v2
	v_mov_b32_e32 v40, v2
	v_mov_b32_e32 v41, v2
	v_mov_b32_e32 v42, v2
	v_mov_b32_e32 v43, v2
	v_mov_b32_e32 v44, v2
	v_mov_b32_e32 v45, v2
	v_mov_b32_e32 v46, v2
	v_mov_b32_e32 v47, v2
	v_mov_b32_e32 v48, v2
	v_mov_b32_e32 v49, v2
	v_mov_b32_e32 v50, v2
	v_mov_b32_e32 v51, v2
	v_mov_b32_e32 v52, v2
	v_mov_b32_e32 v53, v2
	v_mov_b32_e32 v54, v2
	v_mov_b32_e32 v55, v2
	v_mov_b32_e32 v56, v2
	v_mov_b32_e32 v57, v2
	v_mov_b32_e32 v58, v2
	v_mov_b32_e32 v59, v2
	v_mov_b32_e32 v60, v2
	v_mov_b32_e32 v61, v2
	v_mov_b32_e32 v85, v2
	v_mov_b32_e32 v86, v2
	v_mov_b32_e32 v87, v2
	v_mov_b32_e32 v88, v2
	v_mov_b32_e32 v89, v2
	v_mov_b32_e32 v90, v2
	v_mov_b32_e32 v91, v2
	v_mov_b32_e32 v92, v2
	v_mov_b32_e32 v93, v2
	v_mov_b32_e32 v94, v2
	v_mov_b32_e32 v95, v2
	v_mov_b32_e32 v96, v2
	v_mov_b32_e32 v97, v2
	v_mov_b32_e32 v98, v2
	v_mov_b32_e32 v99, v2
	v_mov_b32_e32 v100, v2
	v_mov_b32_e32 v101, v2
	v_mov_b32_e32 v102, v2
	v_mov_b32_e32 v103, v2
	v_mov_b32_e32 v104, v2
	v_mov_b32_e32 v105, v2
	v_mov_b32_e32 v106, v2
	v_mov_b32_e32 v107, v2
	v_mov_b32_e32 v108, v2
	v_mov_b32_e32 v109, v2
	v_mov_b32_e32 v110, v2
	v_mov_b32_e32 v111, v2
	v_mov_b32_e32 v112, v2
	v_mov_b32_e32 v113, v2
	v_mov_b32_e32 v114, v2
	v_mov_b32_e32 v115, v2
	v_mov_b32_e32 v116, v2
	v_mov_b32_e32 v117, v2
	v_mov_b32_e32 v118, v2
	v_mov_b32_e32 v119, v2
	v_mov_b32_e32 v120, v2
	v_mov_b32_e32 v121, v2
	v_mov_b32_e32 v122, v2
	v_mov_b32_e32 v123, v2
	v_mov_b32_e32 v124, v2
	v_mov_b32_e32 v125, v2
	v_mov_b32_e32 v126, v2
	v_mov_b32_e32 v127, v2
	v_mov_b32_e32 v128, v2
	v_mov_b32_e32 v129, v2
	s_waitcnt lgkmcnt(0)
	s_barrier
	s_movk_i32 s97, 0x70
	v_readfirstlane_b32 s98, v136
	v_readfirstlane_b32 s99, v137
	v_subrev_u32_e32 v248, s98, v136
	v_bfi_b32 v248, s97, v146, v248
	v_add_u32_e32 v140, s15, v248
	v_add_u32_e32 v152, s16, v248
	v_add_u32_e32 v156, s17, v248
	v_add_u32_e32 v160, s28, v248
	s_add_u32 s98, s98, s8
	s_addc_u32 s99, s99, s9
	s_add_u32 s98, s98, 0x80
	s_addc_u32 s99, s99, 0
	v_readfirstlane_b32 s100, v138
	v_readfirstlane_b32 s101, v139
	v_subrev_u32_e32 v250, s100, v138
	v_bfi_b32 v250, s97, v146, v250
	v_add_u32_e32 v164, s29, v250
	v_add_u32_e32 v168, s38, v250
	v_add_u32_e32 v172, s39, v250
	v_add_u32_e32 v176, s42, v250
	s_add_u32 s100, s100, s8
	s_addc_u32 s101, s101, s9
	s_add_u32 s100, s100, 0x80
	s_addc_u32 s101, s101, 0
	v_readfirstlane_b32 s96, v146
	s_and_b32 s96, s96, 0xfc00
	s_add_u32 m0, s96, 0x8000
	s_nop 0
	global_load_lds_dwordx4 v140, s[98:99]
	s_add_u32 m0, m0, 0x2000
	s_nop 0
	global_load_lds_dwordx4 v152, s[98:99]
	s_add_u32 m0, m0, 0x2000
	s_nop 0
	global_load_lds_dwordx4 v156, s[98:99]
	s_add_u32 m0, m0, 0x2000
	s_nop 0
	global_load_lds_dwordx4 v160, s[98:99]
	s_add_u32 m0, m0, 0xa000
	s_nop 0
	global_load_lds_dwordx4 v164, s[100:101]
	s_add_u32 m0, m0, 0x2000
	s_nop 0
	global_load_lds_dwordx4 v168, s[100:101]
	s_add_u32 m0, m0, 0x2000
	s_nop 0
	global_load_lds_dwordx4 v172, s[100:101]
	s_add_u32 m0, m0, 0x2000
	s_nop 0
	global_load_lds_dwordx4 v176, s[100:101]
	ds_read_b128 v[180:183], v148
	ds_read_b128 v[184:187], v148 offset:2048
	ds_read_b128 v[188:191], v148 offset:4096
	ds_read_b128 v[192:195], v148 offset:6144
	ds_read_b128 v[212:215], v149
	ds_read_b128 v[218:221], v149 offset:2048
	ds_read_b128 v[224:227], v149 offset:4096
	ds_read_b128 v[228:231], v149 offset:6144
.Lg2_p4_loop:
	ds_read_b128 v[196:199], v148 offset:8192
	ds_read_b128 v[200:203], v148 offset:10240
	ds_read_b128 v[204:207], v148 offset:12288
	ds_read_b128 v[208:211], v148 offset:14336
	s_waitcnt lgkmcnt(4)
	v_mfma_f32_16x16x32_bf16 v[126:129], v[212:215], v[180:183], v[126:129]
	v_mfma_f32_16x16x32_bf16 v[122:125], v[218:221], v[180:183], v[122:125]
	v_mfma_f32_16x16x32_bf16 v[118:121], v[224:227], v[180:183], v[118:121]
	v_mfma_f32_16x16x32_bf16 v[114:117], v[228:231], v[180:183], v[114:117]
	v_mfma_f32_16x16x32_bf16 v[110:113], v[212:215], v[184:187], v[110:113]
	v_mfma_f32_16x16x32_bf16 v[106:109], v[218:221], v[184:187], v[106:109]
	v_mfma_f32_16x16x32_bf16 v[102:105], v[224:227], v[184:187], v[102:105]
	v_mfma_f32_16x16x32_bf16 v[98:101], v[228:231], v[184:187], v[98:101]
	v_mfma_f32_16x16x32_bf16 v[94:97], v[212:215], v[188:191], v[94:97]
	v_mfma_f32_16x16x32_bf16 v[90:93], v[218:221], v[188:191], v[90:93]
	v_mfma_f32_16x16x32_bf16 v[86:89], v[224:227], v[188:191], v[86:89]
	v_mfma_f32_16x16x32_bf16 v[82:85], v[228:231], v[188:191], v[82:85]
	v_mfma_f32_16x16x32_bf16 v[78:81], v[212:215], v[192:195], v[78:81]
	v_mfma_f32_16x16x32_bf16 v[74:77], v[218:221], v[192:195], v[74:77]
	v_mfma_f32_16x16x32_bf16 v[70:73], v[224:227], v[192:195], v[70:73]
	v_mfma_f32_16x16x32_bf16 v[66:69], v[228:231], v[192:195], v[66:69]
	ds_read_b128 v[180:183], v216
	ds_read_b128 v[184:187], v216 offset:2048
	ds_read_b128 v[188:191], v216 offset:4096
	ds_read_b128 v[192:195], v216 offset:6144
	ds_read_b128 v[232:235], v217
	ds_read_b128 v[236:239], v217 offset:2048
	ds_read_b128 v[240:243], v217 offset:4096
	ds_read_b128 v[244:247], v217 offset:6144
	s_waitcnt lgkmcnt(8)
	v_mfma_f32_16x16x32_bf16 v[62:65], v[212:215], v[196:199], v[62:65]
	v_mfma_f32_16x16x32_bf16 v[58:61], v[218:221], v[196:199], v[58:61]
	v_mfma_f32_16x16x32_bf16 v[54:57], v[224:227], v[196:199], v[54:57]
	v_mfma_f32_16x16x32_bf16 v[50:53], v[228:231], v[196:199], v[50:53]
	v_mfma_f32_16x16x32_bf16 v[46:49], v[212:215], v[200:203], v[46:49]
	v_mfma_f32_16x16x32_bf16 v[42:45], v[218:221], v[200:203], v[42:45]
	v_mfma_f32_16x16x32_bf16 v[38:41], v[224:227], v[200:203], v[38:41]
	v_mfma_f32_16x16x32_bf16 v[34:37], v[228:231], v[200:203], v[34:37]
	v_mfma_f32_16x16x32_bf16 v[30:33], v[212:215], v[204:207], v[30:33]
	v_mfma_f32_16x16x32_bf16 v[26:29], v[218:221], v[204:207], v[26:29]
	v_mfma_f32_16x16x32_bf16 v[22:25], v[224:227], v[204:207], v[22:25]
	v_mfma_f32_16x16x32_bf16 v[18:21], v[228:231], v[204:207], v[18:21]
	v_mfma_f32_16x16x32_bf16 v[14:17], v[212:215], v[208:211], v[14:17]
	v_mfma_f32_16x16x32_bf16 v[10:13], v[218:221], v[208:211], v[10:13]
	v_mfma_f32_16x16x32_bf16 v[6:9], v[224:227], v[208:211], v[6:9]
	v_mfma_f32_16x16x32_bf16 v[2:5], v[228:231], v[208:211], v[2:5]
	ds_read_b128 v[196:199], v216 offset:8192
	ds_read_b128 v[200:203], v216 offset:10240
	ds_read_b128 v[204:207], v216 offset:12288
	ds_read_b128 v[208:211], v216 offset:14336
	s_waitcnt lgkmcnt(4)
	v_mfma_f32_16x16x32_bf16 v[126:129], v[232:235], v[180:183], v[126:129]
	v_mfma_f32_16x16x32_bf16 v[122:125], v[236:239], v[180:183], v[122:125]
	v_mfma_f32_16x16x32_bf16 v[118:121], v[240:243], v[180:183], v[118:121]
	v_mfma_f32_16x16x32_bf16 v[114:117], v[244:247], v[180:183], v[114:117]
	v_mfma_f32_16x16x32_bf16 v[110:113], v[232:235], v[184:187], v[110:113]
	v_mfma_f32_16x16x32_bf16 v[106:109], v[236:239], v[184:187], v[106:109]
	v_mfma_f32_16x16x32_bf16 v[102:105], v[240:243], v[184:187], v[102:105]
	v_mfma_f32_16x16x32_bf16 v[98:101], v[244:247], v[184:187], v[98:101]
	v_mfma_f32_16x16x32_bf16 v[94:97], v[232:235], v[188:191], v[94:97]
	v_mfma_f32_16x16x32_bf16 v[90:93], v[236:239], v[188:191], v[90:93]
	v_mfma_f32_16x16x32_bf16 v[86:89], v[240:243], v[188:191], v[86:89]
	v_mfma_f32_16x16x32_bf16 v[82:85], v[244:247], v[188:191], v[82:85]
	v_mfma_f32_16x16x32_bf16 v[78:81], v[232:235], v[192:195], v[78:81]
	v_mfma_f32_16x16x32_bf16 v[74:77], v[236:239], v[192:195], v[74:77]
	v_mfma_f32_16x16x32_bf16 v[70:73], v[240:243], v[192:195], v[70:73]
	v_mfma_f32_16x16x32_bf16 v[66:69], v[244:247], v[192:195], v[66:69]
	s_waitcnt vmcnt(0)
	s_waitcnt lgkmcnt(0)
	s_barrier
	s_add_u32 s8, s8, 0x80
	s_addc_u32 s9, s9, 0
	s_add_u32 s98, s98, 0x80
	s_addc_u32 s99, s99, 0
	s_add_u32 s100, s100, 0x80
	s_addc_u32 s101, s101, 0
	s_cmpk_eq_i32 s8, 0x780
	s_cbranch_scc1 .Lg2_p4_tail
	ds_read_b128 v[180:183], v148 offset:32768
	ds_read_b128 v[184:187], v148 offset:34816
	ds_read_b128 v[188:191], v148 offset:36864
	ds_read_b128 v[192:195], v148 offset:38912
	ds_read_b128 v[212:215], v149 offset:32768
	ds_read_b128 v[218:221], v149 offset:34816
	ds_read_b128 v[224:227], v149 offset:36864
	ds_read_b128 v[228:231], v149 offset:38912
	v_mfma_f32_16x16x32_bf16 v[62:65], v[232:235], v[196:199], v[62:65]
	s_mov_b32 m0, s96
	v_mfma_f32_16x16x32_bf16 v[58:61], v[236:239], v[196:199], v[58:61]
	global_load_lds_dwordx4 v140, s[98:99]
	v_mfma_f32_16x16x32_bf16 v[54:57], v[240:243], v[196:199], v[54:57]
	s_add_u32 m0, m0, 0x2000
	v_mfma_f32_16x16x32_bf16 v[50:53], v[244:247], v[196:199], v[50:53]
	global_load_lds_dwordx4 v152, s[98:99]
	v_mfma_f32_16x16x32_bf16 v[46:49], v[232:235], v[200:203], v[46:49]
	s_add_u32 m0, m0, 0x2000
	v_mfma_f32_16x16x32_bf16 v[42:45], v[236:239], v[200:203], v[42:45]
	global_load_lds_dwordx4 v156, s[98:99]
	v_mfma_f32_16x16x32_bf16 v[38:41], v[240:243], v[200:203], v[38:41]
	s_add_u32 m0, m0, 0x2000
	v_mfma_f32_16x16x32_bf16 v[34:37], v[244:247], v[200:203], v[34:37]
	global_load_lds_dwordx4 v160, s[98:99]
	v_mfma_f32_16x16x32_bf16 v[30:33], v[232:235], v[204:207], v[30:33]
	s_add_u32 m0, m0, 0xa000
	v_mfma_f32_16x16x32_bf16 v[26:29], v[236:239], v[204:207], v[26:29]
	global_load_lds_dwordx4 v164, s[100:101]
	v_mfma_f32_16x16x32_bf16 v[22:25], v[240:243], v[204:207], v[22:25]
	s_add_u32 m0, m0, 0x2000
	v_mfma_f32_16x16x32_bf16 v[18:21], v[244:247], v[204:207], v[18:21]
	global_load_lds_dwordx4 v168, s[100:101]
	v_mfma_f32_16x16x32_bf16 v[14:17], v[232:235], v[208:211], v[14:17]
	s_add_u32 m0, m0, 0x2000
	v_mfma_f32_16x16x32_bf16 v[10:13], v[236:239], v[208:211], v[10:13]
	global_load_lds_dwordx4 v172, s[100:101]
	v_mfma_f32_16x16x32_bf16 v[6:9], v[240:243], v[208:211], v[6:9]
	s_add_u32 m0, m0, 0x2000
	v_mfma_f32_16x16x32_bf16 v[2:5], v[244:247], v[208:211], v[2:5]
	global_load_lds_dwordx4 v176, s[100:101]
	ds_read_b128 v[196:199], v148 offset:40960
	ds_read_b128 v[200:203], v148 offset:43008
	ds_read_b128 v[204:207], v148 offset:45056
	ds_read_b128 v[208:211], v148 offset:47104
	s_waitcnt lgkmcnt(4)
	v_mfma_f32_16x16x32_bf16 v[126:129], v[212:215], v[180:183], v[126:129]
	v_mfma_f32_16x16x32_bf16 v[122:125], v[218:221], v[180:183], v[122:125]
	v_mfma_f32_16x16x32_bf16 v[118:121], v[224:227], v[180:183], v[118:121]
	v_mfma_f32_16x16x32_bf16 v[114:117], v[228:231], v[180:183], v[114:117]
	v_mfma_f32_16x16x32_bf16 v[110:113], v[212:215], v[184:187], v[110:113]
	v_mfma_f32_16x16x32_bf16 v[106:109], v[218:221], v[184:187], v[106:109]
	v_mfma_f32_16x16x32_bf16 v[102:105], v[224:227], v[184:187], v[102:105]
	v_mfma_f32_16x16x32_bf16 v[98:101], v[228:231], v[184:187], v[98:101]
	v_mfma_f32_16x16x32_bf16 v[94:97], v[212:215], v[188:191], v[94:97]
	v_mfma_f32_16x16x32_bf16 v[90:93], v[218:221], v[188:191], v[90:93]
	v_mfma_f32_16x16x32_bf16 v[86:89], v[224:227], v[188:191], v[86:89]
	v_mfma_f32_16x16x32_bf16 v[82:85], v[228:231], v[188:191], v[82:85]
	v_mfma_f32_16x16x32_bf16 v[78:81], v[212:215], v[192:195], v[78:81]
	v_mfma_f32_16x16x32_bf16 v[74:77], v[218:221], v[192:195], v[74:77]
	v_mfma_f32_16x16x32_bf16 v[70:73], v[224:227], v[192:195], v[70:73]
	v_mfma_f32_16x16x32_bf16 v[66:69], v[228:231], v[192:195], v[66:69]
	ds_read_b128 v[180:183], v216 offset:32768
	ds_read_b128 v[184:187], v216 offset:34816
	ds_read_b128 v[188:191], v216 offset:36864
	ds_read_b128 v[192:195], v216 offset:38912
	ds_read_b128 v[232:235], v217 offset:32768
	ds_read_b128 v[236:239], v217 offset:34816
	ds_read_b128 v[240:243], v217 offset:36864
	ds_read_b128 v[244:247], v217 offset:38912
	s_waitcnt lgkmcnt(8)
	v_mfma_f32_16x16x32_bf16 v[62:65], v[212:215], v[196:199], v[62:65]
	v_mfma_f32_16x16x32_bf16 v[58:61], v[218:221], v[196:199], v[58:61]
	v_mfma_f32_16x16x32_bf16 v[54:57], v[224:227], v[196:199], v[54:57]
	v_mfma_f32_16x16x32_bf16 v[50:53], v[228:231], v[196:199], v[50:53]
	v_mfma_f32_16x16x32_bf16 v[46:49], v[212:215], v[200:203], v[46:49]
	v_mfma_f32_16x16x32_bf16 v[42:45], v[218:221], v[200:203], v[42:45]
	v_mfma_f32_16x16x32_bf16 v[38:41], v[224:227], v[200:203], v[38:41]
	v_mfma_f32_16x16x32_bf16 v[34:37], v[228:231], v[200:203], v[34:37]
	v_mfma_f32_16x16x32_bf16 v[30:33], v[212:215], v[204:207], v[30:33]
	v_mfma_f32_16x16x32_bf16 v[26:29], v[218:221], v[204:207], v[26:29]
	v_mfma_f32_16x16x32_bf16 v[22:25], v[224:227], v[204:207], v[22:25]
	v_mfma_f32_16x16x32_bf16 v[18:21], v[228:231], v[204:207], v[18:21]
	v_mfma_f32_16x16x32_bf16 v[14:17], v[212:215], v[208:211], v[14:17]
	v_mfma_f32_16x16x32_bf16 v[10:13], v[218:221], v[208:211], v[10:13]
	v_mfma_f32_16x16x32_bf16 v[6:9], v[224:227], v[208:211], v[6:9]
	v_mfma_f32_16x16x32_bf16 v[2:5], v[228:231], v[208:211], v[2:5]
	ds_read_b128 v[196:199], v216 offset:40960
	ds_read_b128 v[200:203], v216 offset:43008
	ds_read_b128 v[204:207], v216 offset:45056
	ds_read_b128 v[208:211], v216 offset:47104
	s_waitcnt lgkmcnt(4)
	v_mfma_f32_16x16x32_bf16 v[126:129], v[232:235], v[180:183], v[126:129]
	v_mfma_f32_16x16x32_bf16 v[122:125], v[236:239], v[180:183], v[122:125]
	v_mfma_f32_16x16x32_bf16 v[118:121], v[240:243], v[180:183], v[118:121]
	v_mfma_f32_16x16x32_bf16 v[114:117], v[244:247], v[180:183], v[114:117]
	v_mfma_f32_16x16x32_bf16 v[110:113], v[232:235], v[184:187], v[110:113]
	v_mfma_f32_16x16x32_bf16 v[106:109], v[236:239], v[184:187], v[106:109]
	v_mfma_f32_16x16x32_bf16 v[102:105], v[240:243], v[184:187], v[102:105]
	v_mfma_f32_16x16x32_bf16 v[98:101], v[244:247], v[184:187], v[98:101]
	v_mfma_f32_16x16x32_bf16 v[94:97], v[232:235], v[188:191], v[94:97]
	v_mfma_f32_16x16x32_bf16 v[90:93], v[236:239], v[188:191], v[90:93]
	v_mfma_f32_16x16x32_bf16 v[86:89], v[240:243], v[188:191], v[86:89]
	v_mfma_f32_16x16x32_bf16 v[82:85], v[244:247], v[188:191], v[82:85]
	v_mfma_f32_16x16x32_bf16 v[78:81], v[232:235], v[192:195], v[78:81]
	v_mfma_f32_16x16x32_bf16 v[74:77], v[236:239], v[192:195], v[74:77]
	v_mfma_f32_16x16x32_bf16 v[70:73], v[240:243], v[192:195], v[70:73]
	v_mfma_f32_16x16x32_bf16 v[66:69], v[244:247], v[192:195], v[66:69]
	s_waitcnt vmcnt(0)
	s_waitcnt lgkmcnt(0)
	s_barrier
	s_add_u32 s8, s8, 0x80
	s_addc_u32 s9, s9, 0
	s_add_u32 s98, s98, 0x80
	s_addc_u32 s99, s99, 0
	s_add_u32 s100, s100, 0x80
	s_addc_u32 s101, s101, 0
	s_cmpk_eq_i32 s8, 0x780
	s_cbranch_scc1 .Lg2_p4_tail
	ds_read_b128 v[180:183], v148
	ds_read_b128 v[184:187], v148 offset:2048
	ds_read_b128 v[188:191], v148 offset:4096
	ds_read_b128 v[192:195], v148 offset:6144
	ds_read_b128 v[212:215], v149
	ds_read_b128 v[218:221], v149 offset:2048
	ds_read_b128 v[224:227], v149 offset:4096
	ds_read_b128 v[228:231], v149 offset:6144
	v_mfma_f32_16x16x32_bf16 v[62:65], v[232:235], v[196:199], v[62:65]
	s_add_u32 m0, s96, 0x8000
	v_mfma_f32_16x16x32_bf16 v[58:61], v[236:239], v[196:199], v[58:61]
	global_load_lds_dwordx4 v140, s[98:99]
	v_mfma_f32_16x16x32_bf16 v[54:57], v[240:243], v[196:199], v[54:57]
	s_add_u32 m0, m0, 0x2000
	v_mfma_f32_16x16x32_bf16 v[50:53], v[244:247], v[196:199], v[50:53]
	global_load_lds_dwordx4 v152, s[98:99]
	v_mfma_f32_16x16x32_bf16 v[46:49], v[232:235], v[200:203], v[46:49]
	s_add_u32 m0, m0, 0x2000
	v_mfma_f32_16x16x32_bf16 v[42:45], v[236:239], v[200:203], v[42:45]
	global_load_lds_dwordx4 v156, s[98:99]
	v_mfma_f32_16x16x32_bf16 v[38:41], v[240:243], v[200:203], v[38:41]
	s_add_u32 m0, m0, 0x2000
	v_mfma_f32_16x16x32_bf16 v[34:37], v[244:247], v[200:203], v[34:37]
	global_load_lds_dwordx4 v160, s[98:99]
	v_mfma_f32_16x16x32_bf16 v[30:33], v[232:235], v[204:207], v[30:33]
	s_add_u32 m0, m0, 0xa000
	v_mfma_f32_16x16x32_bf16 v[26:29], v[236:239], v[204:207], v[26:29]
	global_load_lds_dwordx4 v164, s[100:101]
	v_mfma_f32_16x16x32_bf16 v[22:25], v[240:243], v[204:207], v[22:25]
	s_add_u32 m0, m0, 0x2000
	v_mfma_f32_16x16x32_bf16 v[18:21], v[244:247], v[204:207], v[18:21]
	global_load_lds_dwordx4 v168, s[100:101]
	v_mfma_f32_16x16x32_bf16 v[14:17], v[232:235], v[208:211], v[14:17]
	s_add_u32 m0, m0, 0x2000
	v_mfma_f32_16x16x32_bf16 v[10:13], v[236:239], v[208:211], v[10:13]
	global_load_lds_dwordx4 v172, s[100:101]
	v_mfma_f32_16x16x32_bf16 v[6:9], v[240:243], v[208:211], v[6:9]
	s_add_u32 m0, m0, 0x2000
	v_mfma_f32_16x16x32_bf16 v[2:5], v[244:247], v[208:211], v[2:5]
	global_load_lds_dwordx4 v176, s[100:101]
	s_branch .Lg2_p4_loop

.LBB0_354:
	s_mul_hi_i32 s0, s3, 0x2e8ba2e9
	s_lshr_b32 s1, s0, 31
	s_ashr_i32 s0, s0, 4
	s_add_i32 s40, s0, s1
	s_lshl_b32 s0, s40, 2
	s_sub_i32 s1, 33, s0
	s_min_u32 s1, s1, 4
	v_cvt_f32_ubyte0_e32 v2, s1
	v_rcp_iflag_f32_e32 v2, v2
	s_sub_i32 s41, 0, s1
	s_mul_i32 s37, s40, 0xffffffa8
	s_add_i32 s37, s37, s3
	v_mul_f32_e32 v2, 0x4f7ffffe, v2
	v_cvt_u32_f32_e32 v2, v2
	s_abs_i32 s39, s37
	s_ashr_i32 s38, s37, 31
	s_mulk_i32 s40, 0x54
	v_readfirstlane_b32 s42, v2
	s_mul_i32 s41, s41, s42
	s_mul_hi_u32 s41, s42, s41
	s_add_i32 s42, s42, s41
	s_mul_hi_u32 s41, s39, s42
	s_mul_i32 s42, s41, s1
	s_sub_i32 s39, s39, s42
	s_add_i32 s42, s41, 1
	s_sub_i32 s43, s39, s1
	s_cmp_ge_u32 s39, s1
	s_cselect_b32 s41, s42, s41
	s_cselect_b32 s39, s43, s39
	s_add_i32 s42, s41, 1
	s_cmp_ge_u32 s39, s1
	s_cselect_b32 s39, s42, s41
	s_xor_b32 s39, s39, s38
	s_sub_i32 s38, s39, s38
	s_add_i32 s0, s0, s6
	s_mul_i32 s41, s1, s38
	s_add_i32 s0, s0, s37
	s_sub_i32 s0, s0, s41
	s_lshl_b32 s37, s0, 8
	v_or_b32_e32 v2, s37, v1
	v_ashrrev_i32_e32 v3, 31, v2
	v_lshlrev_b64 v[2:3], 11, v[2:3]
	v_lshl_add_u64 v[2:3], v[132:133], 0, v[2:3]
	v_add_co_u32_e32 v6, vcc, s9, v2
	s_lshl_b32 s38, s38, 8
	s_nop 0
	v_addc_co_u32_e32 v7, vcc, 0, v3, vcc
	v_or_b32_e32 v4, s38, v1
	global_load_dwordx4 v[20:23], v[2:3], off
	global_load_dwordx4 v[24:27], v[6:7], off
	v_add_co_u32_e32 v6, vcc, s10, v2
	v_ashrrev_i32_e32 v5, 31, v4
	s_nop 0
	v_addc_co_u32_e32 v7, vcc, 0, v3, vcc
	v_lshlrev_b64 v[52:53], 11, v[4:5]
	v_add_co_u32_e32 v2, vcc, s11, v2
	v_lshl_add_u64 v[4:5], v[134:135], 0, v[52:53]
	s_nop 0
	v_addc_co_u32_e32 v3, vcc, 0, v3, vcc
	global_load_dwordx4 v[28:31], v[6:7], off
	global_load_dwordx4 v[32:35], v[2:3], off
	v_add_co_u32_e32 v2, vcc, s9, v4
	s_waitcnt vmcnt(63) expcnt(7) lgkmcnt(15)
	s_nop 0
	v_addc_co_u32_e32 v3, vcc, 0, v5, vcc
	s_barrier
	global_load_dwordx4 v[36:39], v[4:5], off
	global_load_dwordx4 v[40:43], v[2:3], off
	v_add_co_u32_e32 v2, vcc, s10, v4
	s_sub_i32 s41, s8, s41
	s_nop 0
	v_addc_co_u32_e32 v3, vcc, 0, v5, vcc
	v_add_co_u32_e32 v4, vcc, s11, v4
	s_sub_i32 s40, s41, s40
	s_nop 0
	v_addc_co_u32_e32 v5, vcc, 0, v5, vcc
	global_load_dwordx4 v[44:47], v[2:3], off
	global_load_dwordx4 v[48:51], v[4:5], off
	v_lshl_add_u32 v54, s40, 8, v1
	v_ashrrev_i32_e32 v55, 31, v54
	v_lshl_add_u64 v[140:141], v[138:139], 0, v[52:53]
	v_lshlrev_b64 v[52:53], 11, v[54:55]
	s_mov_b64 s[0:1], 0
	s_mov_b32 s39, 0
	v_mov_b32_e32 v2, 0
	v_mov_b32_e32 v3, v131
	v_mov_b32_e32 v4, v131
	v_mov_b32_e32 v5, v131
	v_mov_b32_e32 v6, 0
	v_mov_b32_e32 v7, v131
	v_mov_b32_e32 v8, v131
	v_mov_b32_e32 v9, v131
	v_mov_b32_e32 v10, 0
	v_mov_b32_e32 v11, v131
	v_mov_b32_e32 v12, v131
	v_mov_b32_e32 v13, v131
	v_mov_b32_e32 v14, 0
	v_mov_b32_e32 v15, v131
	v_mov_b32_e32 v16, v131
	v_mov_b32_e32 v17, v131
	v_mov_b32_e32 v18, 0
	v_lshl_add_u64 v[142:143], v[138:139], 0, v[52:53]
	v_mov_b32_e32 v19, v131
	v_mov_b32_e32 v52, v131
	v_mov_b32_e32 v53, v131
	v_mov_b32_e32 v54, 0
	v_mov_b32_e32 v55, v131
	v_mov_b32_e32 v56, v131
	v_mov_b32_e32 v57, v131
	v_mov_b32_e32 v58, 0
	v_mov_b32_e32 v59, v131
	v_mov_b32_e32 v60, v131
	v_mov_b32_e32 v61, v131
	v_mov_b32_e32 v62, 0
	v_mov_b32_e32 v63, v131
	v_mov_b32_e32 v64, v131
	v_mov_b32_e32 v65, v131
	v_mov_b32_e32 v66, 0
	v_mov_b32_e32 v67, v131
	v_mov_b32_e32 v68, v131
	v_mov_b32_e32 v69, v131
	v_mov_b32_e32 v70, 0
	v_mov_b32_e32 v71, v131
	v_mov_b32_e32 v72, v131
	v_mov_b32_e32 v73, v131
	v_mov_b32_e32 v74, 0
	s_waitcnt vmcnt(7)
	ds_write_b128 v144, v[20:23]
	s_waitcnt vmcnt(6)
	ds_write_b128 v144, v[24:27] offset:8192
	s_waitcnt vmcnt(5)
	ds_write_b128 v144, v[28:31] offset:16384
	s_waitcnt vmcnt(4)
	ds_write_b128 v144, v[32:35] offset:24576
	s_waitcnt vmcnt(3)
	ds_write_b128 v145, v[36:39]
	s_waitcnt vmcnt(2)
	ds_write_b128 v145, v[40:43] offset:8192
	s_waitcnt vmcnt(1)
	ds_write_b128 v145, v[44:47] offset:16384
	s_waitcnt vmcnt(0)
	ds_write_b128 v145, v[48:51] offset:24576
	v_mov_b32_e32 v20, v131
	v_mov_b32_e32 v21, v131
	v_mov_b32_e32 v22, 0
	v_mov_b32_e32 v23, v131
	v_mov_b32_e32 v24, v131
	v_mov_b32_e32 v25, v131
	v_mov_b32_e32 v26, 0
	v_mov_b32_e32 v27, v131
	v_mov_b32_e32 v28, v131
	v_mov_b32_e32 v29, v131
	v_mov_b32_e32 v30, 0
	v_mov_b32_e32 v31, v131
	v_mov_b32_e32 v32, v131
	v_mov_b32_e32 v33, v131
	v_mov_b32_e32 v34, 0
	v_mov_b32_e32 v35, v131
	v_mov_b32_e32 v36, v131
	v_mov_b32_e32 v37, v131
	v_mov_b32_e32 v38, 0
	v_mov_b32_e32 v39, v131
	v_mov_b32_e32 v40, v131
	v_mov_b32_e32 v41, v131
	v_mov_b32_e32 v42, 0
	v_mov_b32_e32 v43, v131
	v_mov_b32_e32 v44, v131
	v_mov_b32_e32 v45, v131
	v_mov_b32_e32 v46, 0
	v_mov_b32_e32 v47, v131
	v_mov_b32_e32 v48, v131
	v_mov_b32_e32 v49, v131
	v_mov_b32_e32 v50, 0
	v_mov_b32_e32 v51, v131
	v_mov_b32_e32 v75, v131
	v_mov_b32_e32 v76, v131
	v_mov_b32_e32 v77, v131
	v_mov_b32_e32 v78, 0
	v_mov_b32_e32 v79, v131
	v_mov_b32_e32 v80, v131
	v_mov_b32_e32 v81, v131
	v_mov_b32_e32 v82, 0
	v_mov_b32_e32 v83, v131
	v_mov_b32_e32 v84, v131
	v_mov_b32_e32 v85, v131
	v_mov_b32_e32 v86, 0
	v_mov_b32_e32 v87, v131
	v_mov_b32_e32 v88, v131
	v_mov_b32_e32 v89, v131
	v_mov_b32_e32 v90, 0
	v_mov_b32_e32 v91, v131
	v_mov_b32_e32 v92, v131
	v_mov_b32_e32 v93, v131
	v_mov_b32_e32 v94, 0
	v_mov_b32_e32 v95, v131
	v_mov_b32_e32 v96, v131
	v_mov_b32_e32 v97, v131
	v_mov_b32_e32 v98, 0
	v_mov_b32_e32 v99, v131
	v_mov_b32_e32 v100, v131
	v_mov_b32_e32 v101, v131
	v_mov_b32_e32 v102, 0
	v_mov_b32_e32 v103, v131
	v_mov_b32_e32 v104, v131
	v_mov_b32_e32 v105, v131
	v_mov_b32_e32 v106, 0
	v_mov_b32_e32 v107, v131
	v_mov_b32_e32 v108, v131
	v_mov_b32_e32 v109, v131
	v_mov_b32_e32 v110, 0
	v_mov_b32_e32 v111, v131
	v_mov_b32_e32 v112, v131
	v_mov_b32_e32 v113, v131
	v_mov_b32_e32 v114, 0
	v_mov_b32_e32 v115, v131
	v_mov_b32_e32 v116, v131
	v_mov_b32_e32 v117, v131
	v_mov_b32_e32 v118, 0
	v_mov_b32_e32 v119, v131
	v_mov_b32_e32 v120, v131
	v_mov_b32_e32 v121, v131
	v_mov_b32_e32 v122, 0
	v_mov_b32_e32 v123, v131
	v_mov_b32_e32 v124, v131
	v_mov_b32_e32 v125, v131
	v_mov_b32_e32 v126, 0
	v_mov_b32_e32 v127, v131
	v_mov_b32_e32 v128, v131
	v_mov_b32_e32 v129, v131
	s_waitcnt lgkmcnt(0)
	s_barrier
	s_movk_i32 s97, 0x70
	v_readfirstlane_b32 s98, v142
	v_readfirstlane_b32 s99, v143
	v_subrev_u32_e32 v215, s98, v142
	v_bfi_b32 v215, s97, v144, v215
	v_add_u32_e32 v150, s12, v215
	v_add_u32_e32 v154, s13, v215
	v_add_u32_e32 v158, s14, v215
	v_add_u32_e32 v162, s15, v215
	s_add_u32 s98, s98, s0
	s_addc_u32 s99, s99, s1
	s_add_u32 s98, s98, 0x80
	s_addc_u32 s99, s99, 0
	v_readfirstlane_b32 s100, v140
	v_readfirstlane_b32 s101, v141
	v_subrev_u32_e32 v252, s100, v140
	v_bfi_b32 v252, s97, v144, v252
	v_add_u32_e32 v166, s16, v252
	v_add_u32_e32 v170, s17, v252
	v_add_u32_e32 v174, s28, v252
	v_add_u32_e32 v178, s29, v252
	s_add_u32 s100, s100, s0
	s_addc_u32 s101, s101, s1
	s_add_u32 s100, s100, 0x80
	s_addc_u32 s101, s101, 0
	v_readfirstlane_b32 s96, v144
	s_and_b32 s96, s96, 0xfc00
	s_add_u32 m0, s96, 0x8000
	s_nop 0
	global_load_lds_dwordx4 v150, s[98:99]
	s_add_u32 m0, m0, 0x2000
	s_nop 0
	global_load_lds_dwordx4 v154, s[98:99]
	s_add_u32 m0, m0, 0x2000
	s_nop 0
	global_load_lds_dwordx4 v158, s[98:99]
	s_add_u32 m0, m0, 0x2000
	s_nop 0
	global_load_lds_dwordx4 v162, s[98:99]
	s_add_u32 m0, m0, 0xa000
	s_nop 0
	global_load_lds_dwordx4 v166, s[100:101]
	s_add_u32 m0, m0, 0x2000
	s_nop 0
	global_load_lds_dwordx4 v170, s[100:101]
	s_add_u32 m0, m0, 0x2000
	s_nop 0
	global_load_lds_dwordx4 v174, s[100:101]
	s_add_u32 m0, m0, 0x2000
	s_nop 0
	global_load_lds_dwordx4 v178, s[100:101]
	ds_read_b128 v[182:185], v146
	ds_read_b128 v[186:189], v146 offset:2048
	ds_read_b128 v[190:193], v146 offset:4096
	ds_read_b128 v[194:197], v146 offset:6144
	ds_read_b128 v[218:221], v147
	ds_read_b128 v[224:227], v147 offset:2048
	ds_read_b128 v[228:231], v147 offset:4096
	ds_read_b128 v[232:235], v147 offset:6144
.Lg2_p6_loop:
	ds_read_b128 v[198:201], v146 offset:8192
	ds_read_b128 v[202:205], v146 offset:10240
	ds_read_b128 v[206:209], v146 offset:12288
	ds_read_b128 v[210:213], v146 offset:14336
	s_waitcnt lgkmcnt(4)
	v_mfma_f32_16x16x32_bf16 v[126:129], v[218:221], v[182:185], v[126:129]
	v_mfma_f32_16x16x32_bf16 v[122:125], v[224:227], v[182:185], v[122:125]
	v_mfma_f32_16x16x32_bf16 v[118:121], v[228:231], v[182:185], v[118:121]
	v_mfma_f32_16x16x32_bf16 v[114:117], v[232:235], v[182:185], v[114:117]
	v_mfma_f32_16x16x32_bf16 v[110:113], v[218:221], v[186:189], v[110:113]
	v_mfma_f32_16x16x32_bf16 v[106:109], v[224:227], v[186:189], v[106:109]
	v_mfma_f32_16x16x32_bf16 v[102:105], v[228:231], v[186:189], v[102:105]
	v_mfma_f32_16x16x32_bf16 v[98:101], v[232:235], v[186:189], v[98:101]
	v_mfma_f32_16x16x32_bf16 v[94:97], v[218:221], v[190:193], v[94:97]
	v_mfma_f32_16x16x32_bf16 v[90:93], v[224:227], v[190:193], v[90:93]
	v_mfma_f32_16x16x32_bf16 v[86:89], v[228:231], v[190:193], v[86:89]
	v_mfma_f32_16x16x32_bf16 v[82:85], v[232:235], v[190:193], v[82:85]
	v_mfma_f32_16x16x32_bf16 v[78:81], v[218:221], v[194:197], v[78:81]
	v_mfma_f32_16x16x32_bf16 v[74:77], v[224:227], v[194:197], v[74:77]
	v_mfma_f32_16x16x32_bf16 v[70:73], v[228:231], v[194:197], v[70:73]
	v_mfma_f32_16x16x32_bf16 v[66:69], v[232:235], v[194:197], v[66:69]
	ds_read_b128 v[182:185], v216
	ds_read_b128 v[186:189], v216 offset:2048
	ds_read_b128 v[190:193], v216 offset:4096
	ds_read_b128 v[194:197], v216 offset:6144
	ds_read_b128 v[236:239], v217
	ds_read_b128 v[240:243], v217 offset:2048
	ds_read_b128 v[244:247], v217 offset:4096
	ds_read_b128 v[248:251], v217 offset:6144
	s_waitcnt lgkmcnt(8)
	v_mfma_f32_16x16x32_bf16 v[62:65], v[218:221], v[198:201], v[62:65]
	v_mfma_f32_16x16x32_bf16 v[58:61], v[224:227], v[198:201], v[58:61]
	v_mfma_f32_16x16x32_bf16 v[54:57], v[228:231], v[198:201], v[54:57]
	v_mfma_f32_16x16x32_bf16 v[50:53], v[232:235], v[198:201], v[50:53]
	v_mfma_f32_16x16x32_bf16 v[46:49], v[218:221], v[202:205], v[46:49]
	v_mfma_f32_16x16x32_bf16 v[42:45], v[224:227], v[202:205], v[42:45]
	v_mfma_f32_16x16x32_bf16 v[38:41], v[228:231], v[202:205], v[38:41]
	v_mfma_f32_16x16x32_bf16 v[34:37], v[232:235], v[202:205], v[34:37]
	v_mfma_f32_16x16x32_bf16 v[30:33], v[218:221], v[206:209], v[30:33]
	v_mfma_f32_16x16x32_bf16 v[26:29], v[224:227], v[206:209], v[26:29]
	v_mfma_f32_16x16x32_bf16 v[22:25], v[228:231], v[206:209], v[22:25]
	v_mfma_f32_16x16x32_bf16 v[18:21], v[232:235], v[206:209], v[18:21]
	v_mfma_f32_16x16x32_bf16 v[14:17], v[218:221], v[210:213], v[14:17]
	v_mfma_f32_16x16x32_bf16 v[10:13], v[224:227], v[210:213], v[10:13]
	v_mfma_f32_16x16x32_bf16 v[6:9], v[228:231], v[210:213], v[6:9]
	v_mfma_f32_16x16x32_bf16 v[2:5], v[232:235], v[210:213], v[2:5]
	ds_read_b128 v[198:201], v216 offset:8192
	ds_read_b128 v[202:205], v216 offset:10240
	ds_read_b128 v[206:209], v216 offset:12288
	ds_read_b128 v[210:213], v216 offset:14336
	s_waitcnt lgkmcnt(4)
	v_mfma_f32_16x16x32_bf16 v[126:129], v[236:239], v[182:185], v[126:129]
	v_mfma_f32_16x16x32_bf16 v[122:125], v[240:243], v[182:185], v[122:125]
	v_mfma_f32_16x16x32_bf16 v[118:121], v[244:247], v[182:185], v[118:121]
	v_mfma_f32_16x16x32_bf16 v[114:117], v[248:251], v[182:185], v[114:117]
	v_mfma_f32_16x16x32_bf16 v[110:113], v[236:239], v[186:189], v[110:113]
	v_mfma_f32_16x16x32_bf16 v[106:109], v[240:243], v[186:189], v[106:109]
	v_mfma_f32_16x16x32_bf16 v[102:105], v[244:247], v[186:189], v[102:105]
	v_mfma_f32_16x16x32_bf16 v[98:101], v[248:251], v[186:189], v[98:101]
	v_mfma_f32_16x16x32_bf16 v[94:97], v[236:239], v[190:193], v[94:97]
	v_mfma_f32_16x16x32_bf16 v[90:93], v[240:243], v[190:193], v[90:93]
	v_mfma_f32_16x16x32_bf16 v[86:89], v[244:247], v[190:193], v[86:89]
	v_mfma_f32_16x16x32_bf16 v[82:85], v[248:251], v[190:193], v[82:85]
	v_mfma_f32_16x16x32_bf16 v[78:81], v[236:239], v[194:197], v[78:81]
	v_mfma_f32_16x16x32_bf16 v[74:77], v[240:243], v[194:197], v[74:77]
	v_mfma_f32_16x16x32_bf16 v[70:73], v[244:247], v[194:197], v[70:73]
	v_mfma_f32_16x16x32_bf16 v[66:69], v[248:251], v[194:197], v[66:69]
	s_waitcnt vmcnt(0)
	s_waitcnt lgkmcnt(0)
	s_barrier
	s_add_u32 s0, s0, 0x80
	s_addc_u32 s1, s1, 0
	s_add_u32 s98, s98, 0x80
	s_addc_u32 s99, s99, 0
	s_add_u32 s100, s100, 0x80
	s_addc_u32 s101, s101, 0
	s_cmpk_eq_i32 s0, 0x780
	s_cbranch_scc1 .Lg2_p6_tail
	ds_read_b128 v[182:185], v146 offset:32768
	ds_read_b128 v[186:189], v146 offset:34816
	ds_read_b128 v[190:193], v146 offset:36864
	ds_read_b128 v[194:197], v146 offset:38912
	ds_read_b128 v[218:221], v147 offset:32768
	ds_read_b128 v[224:227], v147 offset:34816
	ds_read_b128 v[228:231], v147 offset:36864
	ds_read_b128 v[232:235], v147 offset:38912
	v_mfma_f32_16x16x32_bf16 v[62:65], v[236:239], v[198:201], v[62:65]
	s_mov_b32 m0, s96
	v_mfma_f32_16x16x32_bf16 v[58:61], v[240:243], v[198:201], v[58:61]
	global_load_lds_dwordx4 v150, s[98:99]
	v_mfma_f32_16x16x32_bf16 v[54:57], v[244:247], v[198:201], v[54:57]
	s_add_u32 m0, m0, 0x2000
	v_mfma_f32_16x16x32_bf16 v[50:53], v[248:251], v[198:201], v[50:53]
	global_load_lds_dwordx4 v154, s[98:99]
	v_mfma_f32_16x16x32_bf16 v[46:49], v[236:239], v[202:205], v[46:49]
	s_add_u32 m0, m0, 0x2000
	v_mfma_f32_16x16x32_bf16 v[42:45], v[240:243], v[202:205], v[42:45]
	global_load_lds_dwordx4 v158, s[98:99]
	v_mfma_f32_16x16x32_bf16 v[38:41], v[244:247], v[202:205], v[38:41]
	s_add_u32 m0, m0, 0x2000
	v_mfma_f32_16x16x32_bf16 v[34:37], v[248:251], v[202:205], v[34:37]
	global_load_lds_dwordx4 v162, s[98:99]
	v_mfma_f32_16x16x32_bf16 v[30:33], v[236:239], v[206:209], v[30:33]
	s_add_u32 m0, m0, 0xa000
	v_mfma_f32_16x16x32_bf16 v[26:29], v[240:243], v[206:209], v[26:29]
	global_load_lds_dwordx4 v166, s[100:101]
	v_mfma_f32_16x16x32_bf16 v[22:25], v[244:247], v[206:209], v[22:25]
	s_add_u32 m0, m0, 0x2000
	v_mfma_f32_16x16x32_bf16 v[18:21], v[248:251], v[206:209], v[18:21]
	global_load_lds_dwordx4 v170, s[100:101]
	v_mfma_f32_16x16x32_bf16 v[14:17], v[236:239], v[210:213], v[14:17]
	s_add_u32 m0, m0, 0x2000
	v_mfma_f32_16x16x32_bf16 v[10:13], v[240:243], v[210:213], v[10:13]
	global_load_lds_dwordx4 v174, s[100:101]
	v_mfma_f32_16x16x32_bf16 v[6:9], v[244:247], v[210:213], v[6:9]
	s_add_u32 m0, m0, 0x2000
	v_mfma_f32_16x16x32_bf16 v[2:5], v[248:251], v[210:213], v[2:5]
	global_load_lds_dwordx4 v178, s[100:101]
	ds_read_b128 v[198:201], v146 offset:40960
	ds_read_b128 v[202:205], v146 offset:43008
	ds_read_b128 v[206:209], v146 offset:45056
	ds_read_b128 v[210:213], v146 offset:47104
	s_waitcnt lgkmcnt(4)
	v_mfma_f32_16x16x32_bf16 v[126:129], v[218:221], v[182:185], v[126:129]
	v_mfma_f32_16x16x32_bf16 v[122:125], v[224:227], v[182:185], v[122:125]
	v_mfma_f32_16x16x32_bf16 v[118:121], v[228:231], v[182:185], v[118:121]
	v_mfma_f32_16x16x32_bf16 v[114:117], v[232:235], v[182:185], v[114:117]
	v_mfma_f32_16x16x32_bf16 v[110:113], v[218:221], v[186:189], v[110:113]
	v_mfma_f32_16x16x32_bf16 v[106:109], v[224:227], v[186:189], v[106:109]
	v_mfma_f32_16x16x32_bf16 v[102:105], v[228:231], v[186:189], v[102:105]
	v_mfma_f32_16x16x32_bf16 v[98:101], v[232:235], v[186:189], v[98:101]
	v_mfma_f32_16x16x32_bf16 v[94:97], v[218:221], v[190:193], v[94:97]
	v_mfma_f32_16x16x32_bf16 v[90:93], v[224:227], v[190:193], v[90:93]
	v_mfma_f32_16x16x32_bf16 v[86:89], v[228:231], v[190:193], v[86:89]
	v_mfma_f32_16x16x32_bf16 v[82:85], v[232:235], v[190:193], v[82:85]
	v_mfma_f32_16x16x32_bf16 v[78:81], v[218:221], v[194:197], v[78:81]
	v_mfma_f32_16x16x32_bf16 v[74:77], v[224:227], v[194:197], v[74:77]
	v_mfma_f32_16x16x32_bf16 v[70:73], v[228:231], v[194:197], v[70:73]
	v_mfma_f32_16x16x32_bf16 v[66:69], v[232:235], v[194:197], v[66:69]
	ds_read_b128 v[182:185], v216 offset:32768
	ds_read_b128 v[186:189], v216 offset:34816
	ds_read_b128 v[190:193], v216 offset:36864
	ds_read_b128 v[194:197], v216 offset:38912
	ds_read_b128 v[236:239], v217 offset:32768
	ds_read_b128 v[240:243], v217 offset:34816
	ds_read_b128 v[244:247], v217 offset:36864
	ds_read_b128 v[248:251], v217 offset:38912
	s_waitcnt lgkmcnt(8)
	v_mfma_f32_16x16x32_bf16 v[62:65], v[218:221], v[198:201], v[62:65]
	v_mfma_f32_16x16x32_bf16 v[58:61], v[224:227], v[198:201], v[58:61]
	v_mfma_f32_16x16x32_bf16 v[54:57], v[228:231], v[198:201], v[54:57]
	v_mfma_f32_16x16x32_bf16 v[50:53], v[232:235], v[198:201], v[50:53]
	v_mfma_f32_16x16x32_bf16 v[46:49], v[218:221], v[202:205], v[46:49]
	v_mfma_f32_16x16x32_bf16 v[42:45], v[224:227], v[202:205], v[42:45]
	v_mfma_f32_16x16x32_bf16 v[38:41], v[228:231], v[202:205], v[38:41]
	v_mfma_f32_16x16x32_bf16 v[34:37], v[232:235], v[202:205], v[34:37]
	v_mfma_f32_16x16x32_bf16 v[30:33], v[218:221], v[206:209], v[30:33]
	v_mfma_f32_16x16x32_bf16 v[26:29], v[224:227], v[206:209], v[26:29]
	v_mfma_f32_16x16x32_bf16 v[22:25], v[228:231], v[206:209], v[22:25]
	v_mfma_f32_16x16x32_bf16 v[18:21], v[232:235], v[206:209], v[18:21]
	v_mfma_f32_16x16x32_bf16 v[14:17], v[218:221], v[210:213], v[14:17]
	v_mfma_f32_16x16x32_bf16 v[10:13], v[224:227], v[210:213], v[10:13]
	v_mfma_f32_16x16x32_bf16 v[6:9], v[228:231], v[210:213], v[6:9]
	v_mfma_f32_16x16x32_bf16 v[2:5], v[232:235], v[210:213], v[2:5]
	ds_read_b128 v[198:201], v216 offset:40960
	ds_read_b128 v[202:205], v216 offset:43008
	ds_read_b128 v[206:209], v216 offset:45056
	ds_read_b128 v[210:213], v216 offset:47104
	s_waitcnt lgkmcnt(4)
	v_mfma_f32_16x16x32_bf16 v[126:129], v[236:239], v[182:185], v[126:129]
	v_mfma_f32_16x16x32_bf16 v[122:125], v[240:243], v[182:185], v[122:125]
	v_mfma_f32_16x16x32_bf16 v[118:121], v[244:247], v[182:185], v[118:121]
	v_mfma_f32_16x16x32_bf16 v[114:117], v[248:251], v[182:185], v[114:117]
	v_mfma_f32_16x16x32_bf16 v[110:113], v[236:239], v[186:189], v[110:113]
	v_mfma_f32_16x16x32_bf16 v[106:109], v[240:243], v[186:189], v[106:109]
	v_mfma_f32_16x16x32_bf16 v[102:105], v[244:247], v[186:189], v[102:105]
	v_mfma_f32_16x16x32_bf16 v[98:101], v[248:251], v[186:189], v[98:101]
	v_mfma_f32_16x16x32_bf16 v[94:97], v[236:239], v[190:193], v[94:97]
	v_mfma_f32_16x16x32_bf16 v[90:93], v[240:243], v[190:193], v[90:93]
	v_mfma_f32_16x16x32_bf16 v[86:89], v[244:247], v[190:193], v[86:89]
	v_mfma_f32_16x16x32_bf16 v[82:85], v[248:251], v[190:193], v[82:85]
	v_mfma_f32_16x16x32_bf16 v[78:81], v[236:239], v[194:197], v[78:81]
	v_mfma_f32_16x16x32_bf16 v[74:77], v[240:243], v[194:197], v[74:77]
	v_mfma_f32_16x16x32_bf16 v[70:73], v[244:247], v[194:197], v[70:73]
	v_mfma_f32_16x16x32_bf16 v[66:69], v[248:251], v[194:197], v[66:69]
	s_waitcnt vmcnt(0)
	s_waitcnt lgkmcnt(0)
	s_barrier
	s_add_u32 s0, s0, 0x80
	s_addc_u32 s1, s1, 0
	s_add_u32 s98, s98, 0x80
	s_addc_u32 s99, s99, 0
	s_add_u32 s100, s100, 0x80
	s_addc_u32 s101, s101, 0
	s_cmpk_eq_i32 s0, 0x780
	s_cbranch_scc1 .Lg2_p6_tail
	ds_read_b128 v[182:185], v146
	ds_read_b128 v[186:189], v146 offset:2048
	ds_read_b128 v[190:193], v146 offset:4096
	ds_read_b128 v[194:197], v146 offset:6144
	ds_read_b128 v[218:221], v147
	ds_read_b128 v[224:227], v147 offset:2048
	ds_read_b128 v[228:231], v147 offset:4096
	ds_read_b128 v[232:235], v147 offset:6144
	v_mfma_f32_16x16x32_bf16 v[62:65], v[236:239], v[198:201], v[62:65]
	s_add_u32 m0, s96, 0x8000
	v_mfma_f32_16x16x32_bf16 v[58:61], v[240:243], v[198:201], v[58:61]
	global_load_lds_dwordx4 v150, s[98:99]
	v_mfma_f32_16x16x32_bf16 v[54:57], v[244:247], v[198:201], v[54:57]
	s_add_u32 m0, m0, 0x2000
	v_mfma_f32_16x16x32_bf16 v[50:53], v[248:251], v[198:201], v[50:53]
	global_load_lds_dwordx4 v154, s[98:99]
	v_mfma_f32_16x16x32_bf16 v[46:49], v[236:239], v[202:205], v[46:49]
	s_add_u32 m0, m0, 0x2000
	v_mfma_f32_16x16x32_bf16 v[42:45], v[240:243], v[202:205], v[42:45]
	global_load_lds_dwordx4 v158, s[98:99]
	v_mfma_f32_16x16x32_bf16 v[38:41], v[244:247], v[202:205], v[38:41]
	s_add_u32 m0, m0, 0x2000
	v_mfma_f32_16x16x32_bf16 v[34:37], v[248:251], v[202:205], v[34:37]
	global_load_lds_dwordx4 v162, s[98:99]
	v_mfma_f32_16x16x32_bf16 v[30:33], v[236:239], v[206:209], v[30:33]
	s_add_u32 m0, m0, 0xa000
	v_mfma_f32_16x16x32_bf16 v[26:29], v[240:243], v[206:209], v[26:29]
	global_load_lds_dwordx4 v166, s[100:101]
	v_mfma_f32_16x16x32_bf16 v[22:25], v[244:247], v[206:209], v[22:25]
	s_add_u32 m0, m0, 0x2000
	v_mfma_f32_16x16x32_bf16 v[18:21], v[248:251], v[206:209], v[18:21]
	global_load_lds_dwordx4 v170, s[100:101]
	v_mfma_f32_16x16x32_bf16 v[14:17], v[236:239], v[210:213], v[14:17]
	s_add_u32 m0, m0, 0x2000
	v_mfma_f32_16x16x32_bf16 v[10:13], v[240:243], v[210:213], v[10:13]
	global_load_lds_dwordx4 v174, s[100:101]
	v_mfma_f32_16x16x32_bf16 v[6:9], v[244:247], v[210:213], v[6:9]
	s_add_u32 m0, m0, 0x2000
	v_mfma_f32_16x16x32_bf16 v[2:5], v[248:251], v[210:213], v[2:5]
	global_load_lds_dwordx4 v178, s[100:101]
	s_branch .Lg2_p6_loop

.LBB0_378:
	s_lshl_b32 s47, s45, 8
	v_or_b32_e32 v27, s47, v1
	v_mad_i64_i32 v[2:3], s[8:9], v27, s12, v[130:131]
	v_add_co_u32_e32 v6, vcc, 0x58000, v2
	s_lshl_b32 s46, s44, 8
	s_nop 0
	v_addc_co_u32_e32 v7, vcc, 0, v3, vcc
	global_load_dwordx4 v[28:31], v[2:3], off
	global_load_dwordx4 v[32:35], v[6:7], off
	v_add_co_u32_e32 v6, vcc, 0xb0000, v2
	v_or_b32_e32 v60, s46, v1
	s_nop 0
	v_addc_co_u32_e32 v7, vcc, 0, v3, vcc
	v_add_co_u32_e32 v2, vcc, 0x108000, v2
	v_mad_i64_i32 v[4:5], s[8:9], v60, s12, v[132:133]
	s_nop 0
	v_addc_co_u32_e32 v3, vcc, 0, v3, vcc
	global_load_dwordx4 v[36:39], v[6:7], off
	global_load_dwordx4 v[40:43], v[2:3], off
	v_add_co_u32_e32 v2, vcc, s13, v4
	s_waitcnt vmcnt(63) expcnt(7) lgkmcnt(15)
	s_nop 0
	v_addc_co_u32_e32 v3, vcc, 0, v5, vcc
	s_barrier
	global_load_dwordx4 v[44:47], v[4:5], off
	global_load_dwordx4 v[48:51], v[2:3], off
	v_add_co_u32_e32 v2, vcc, s14, v4
	s_mov_b32 s52, 0
	s_nop 0
	v_addc_co_u32_e32 v3, vcc, 0, v5, vcc
	v_add_co_u32_e32 v4, vcc, s15, v4
	s_mov_b64 s[8:9], 0
	s_nop 0
	v_addc_co_u32_e32 v5, vcc, 0, v5, vcc
	global_load_dwordx4 v[52:55], v[2:3], off
	global_load_dwordx4 v[56:59], v[4:5], off
	v_mov_b32_e32 v2, 0
	v_mov_b32_e32 v3, v2
	v_mov_b32_e32 v4, v2
	v_mov_b32_e32 v5, v2
	v_mov_b32_e32 v6, v2
	v_mov_b32_e32 v7, v2
	v_mov_b32_e32 v8, v2
	v_mov_b32_e32 v9, v2
	v_mov_b32_e32 v10, v2
	v_mov_b32_e32 v11, v2
	v_mov_b32_e32 v12, v2
	v_mov_b32_e32 v13, v2
	v_mov_b32_e32 v14, v2
	v_mov_b32_e32 v15, v2
	v_mov_b32_e32 v16, v2
	v_mov_b32_e32 v17, v2
	v_mov_b32_e32 v18, v2
	v_mov_b32_e32 v19, v2
	v_mov_b32_e32 v20, v2
	v_mov_b32_e32 v21, v2
	v_mov_b32_e32 v22, v2
	v_mov_b32_e32 v23, v2
	v_mov_b32_e32 v24, v2
	v_mov_b32_e32 v25, v2
	v_mov_b32_e32 v26, v2
	v_mad_i64_i32 v[136:137], s[56:57], v27, s12, v[134:135]
	v_mad_i64_i32 v[138:139], s[56:57], v60, s12, v[134:135]
	v_mov_b32_e32 v27, v2
	v_mov_b32_e32 v60, v2
	v_mov_b32_e32 v61, v2
	v_mov_b32_e32 v62, v2
	v_mov_b32_e32 v63, v2
	v_mov_b32_e32 v64, v2
	v_mov_b32_e32 v65, v2
	v_mov_b32_e32 v66, v2
	v_mov_b32_e32 v67, v2
	v_mov_b32_e32 v68, v2
	v_mov_b32_e32 v69, v2
	v_mov_b32_e32 v70, v2
	v_mov_b32_e32 v71, v2
	v_mov_b32_e32 v72, v2
	v_mov_b32_e32 v73, v2
	v_mov_b32_e32 v74, v2
	v_mov_b32_e32 v75, v2
	v_mov_b32_e32 v76, v2
	v_mov_b32_e32 v77, v2
	v_mov_b32_e32 v78, v2
	v_mov_b32_e32 v79, v2
	v_mov_b32_e32 v80, v2
	v_mov_b32_e32 v81, v2
	v_mov_b32_e32 v82, v2
	s_waitcnt vmcnt(7)
	ds_write_b128 v146, v[28:31]
	s_waitcnt vmcnt(6)
	ds_write_b128 v146, v[32:35] offset:8192
	s_waitcnt vmcnt(5)
	ds_write_b128 v146, v[36:39] offset:16384
	s_waitcnt vmcnt(4)
	ds_write_b128 v146, v[40:43] offset:24576
	s_waitcnt vmcnt(3)
	ds_write_b128 v147, v[44:47]
	s_waitcnt vmcnt(2)
	ds_write_b128 v147, v[48:51] offset:8192
	s_waitcnt vmcnt(1)
	ds_write_b128 v147, v[52:55] offset:16384
	s_waitcnt vmcnt(0)
	ds_write_b128 v147, v[56:59] offset:24576
	v_mov_b32_e32 v28, v2
	v_mov_b32_e32 v29, v2
	v_mov_b32_e32 v30, v2
	v_mov_b32_e32 v31, v2
	v_mov_b32_e32 v32, v2
	v_mov_b32_e32 v33, v2
	v_mov_b32_e32 v34, v2
	v_mov_b32_e32 v35, v2
	v_mov_b32_e32 v36, v2
	v_mov_b32_e32 v37, v2
	v_mov_b32_e32 v38, v2
	v_mov_b32_e32 v39, v2
	v_mov_b32_e32 v40, v2
	v_mov_b32_e32 v41, v2
	v_mov_b32_e32 v42, v2
	v_mov_b32_e32 v43, v2
	v_mov_b32_e32 v44, v2
	v_mov_b32_e32 v45, v2
	v_mov_b32_e32 v46, v2
	v_mov_b32_e32 v47, v2
	v_mov_b32_e32 v48, v2
	v_mov_b32_e32 v49, v2
	v_mov_b32_e32 v50, v2
	v_mov_b32_e32 v51, v2
	v_mov_b32_e32 v52, v2
	v_mov_b32_e32 v53, v2
	v_mov_b32_e32 v54, v2
	v_mov_b32_e32 v55, v2
	v_mov_b32_e32 v56, v2
	v_mov_b32_e32 v57, v2
	v_mov_b32_e32 v58, v2
	v_mov_b32_e32 v59, v2
	v_mov_b32_e32 v83, v2
	v_mov_b32_e32 v84, v2
	v_mov_b32_e32 v85, v2
	v_mov_b32_e32 v86, v2
	v_mov_b32_e32 v87, v2
	v_mov_b32_e32 v88, v2
	v_mov_b32_e32 v89, v2
	v_mov_b32_e32 v90, v2
	v_mov_b32_e32 v91, v2
	v_mov_b32_e32 v92, v2
	v_mov_b32_e32 v93, v2
	v_mov_b32_e32 v94, v2
	v_mov_b32_e32 v95, v2
	v_mov_b32_e32 v96, v2
	v_mov_b32_e32 v97, v2
	v_mov_b32_e32 v98, v2
	v_mov_b32_e32 v99, v2
	v_mov_b32_e32 v100, v2
	v_mov_b32_e32 v101, v2
	v_mov_b32_e32 v102, v2
	v_mov_b32_e32 v103, v2
	v_mov_b32_e32 v104, v2
	v_mov_b32_e32 v105, v2
	v_mov_b32_e32 v106, v2
	v_mov_b32_e32 v107, v2
	v_mov_b32_e32 v108, v2
	v_mov_b32_e32 v109, v2
	v_mov_b32_e32 v110, v2
	v_mov_b32_e32 v111, v2
	v_mov_b32_e32 v112, v2
	v_mov_b32_e32 v113, v2
	v_mov_b32_e32 v114, v2
	v_mov_b32_e32 v115, v2
	v_mov_b32_e32 v116, v2
	v_mov_b32_e32 v117, v2
	v_mov_b32_e32 v118, v2
	v_mov_b32_e32 v119, v2
	v_mov_b32_e32 v120, v2
	v_mov_b32_e32 v121, v2
	v_mov_b32_e32 v122, v2
	v_mov_b32_e32 v123, v2
	v_mov_b32_e32 v124, v2
	v_mov_b32_e32 v125, v2
	v_mov_b32_e32 v126, v2
	v_mov_b32_e32 v127, v2
	v_mov_b32_e32 v128, v2
	v_mov_b32_e32 v129, v2
	s_waitcnt lgkmcnt(0)
	s_barrier
	s_movk_i32 s97, 0x70
	v_readfirstlane_b32 s98, v136
	v_readfirstlane_b32 s99, v137
	v_subrev_u32_e32 v248, s98, v136
	v_bfi_b32 v248, s97, v146, v248
	v_add_u32_e32 v140, s16, v248
	v_add_u32_e32 v152, s17, v248
	v_add_u32_e32 v156, s28, v248
	v_add_u32_e32 v160, s29, v248
	s_add_u32 s98, s98, s8
	s_addc_u32 s99, s99, s9
	s_add_u32 s98, s98, 0x80
	s_addc_u32 s99, s99, 0
	v_readfirstlane_b32 s100, v138
	v_readfirstlane_b32 s101, v139
	v_subrev_u32_e32 v250, s100, v138
	v_bfi_b32 v250, s97, v146, v250
	v_add_u32_e32 v164, s36, v250
	v_add_u32_e32 v168, s37, v250
	v_add_u32_e32 v172, s38, v250
	v_add_u32_e32 v176, s39, v250
	s_add_u32 s100, s100, s8
	s_addc_u32 s101, s101, s9
	s_add_u32 s100, s100, 0x80
	s_addc_u32 s101, s101, 0
	v_readfirstlane_b32 s96, v146
	s_and_b32 s96, s96, 0xfc00
	s_add_u32 m0, s96, 0x8000
	s_nop 0
	global_load_lds_dwordx4 v140, s[98:99]
	s_add_u32 m0, m0, 0x2000
	s_nop 0
	global_load_lds_dwordx4 v152, s[98:99]
	s_add_u32 m0, m0, 0x2000
	s_nop 0
	global_load_lds_dwordx4 v156, s[98:99]
	s_add_u32 m0, m0, 0x2000
	s_nop 0
	global_load_lds_dwordx4 v160, s[98:99]
	s_add_u32 m0, m0, 0xa000
	s_nop 0
	global_load_lds_dwordx4 v164, s[100:101]
	s_add_u32 m0, m0, 0x2000
	s_nop 0
	global_load_lds_dwordx4 v168, s[100:101]
	s_add_u32 m0, m0, 0x2000
	s_nop 0
	global_load_lds_dwordx4 v172, s[100:101]
	s_add_u32 m0, m0, 0x2000
	s_nop 0
	global_load_lds_dwordx4 v176, s[100:101]
	ds_read_b128 v[180:183], v148
	ds_read_b128 v[184:187], v148 offset:2048
	ds_read_b128 v[188:191], v148 offset:4096
	ds_read_b128 v[192:195], v148 offset:6144
	ds_read_b128 v[212:215], v149
	ds_read_b128 v[218:221], v149 offset:2048
	ds_read_b128 v[224:227], v149 offset:4096
	ds_read_b128 v[228:231], v149 offset:6144
.Lg2_p7_loop:
	ds_read_b128 v[196:199], v148 offset:8192
	ds_read_b128 v[200:203], v148 offset:10240
	ds_read_b128 v[204:207], v148 offset:12288
	ds_read_b128 v[208:211], v148 offset:14336
	s_waitcnt lgkmcnt(4)
	v_mfma_f32_16x16x32_bf16 v[126:129], v[212:215], v[180:183], v[126:129]
	v_mfma_f32_16x16x32_bf16 v[122:125], v[218:221], v[180:183], v[122:125]
	v_mfma_f32_16x16x32_bf16 v[118:121], v[224:227], v[180:183], v[118:121]
	v_mfma_f32_16x16x32_bf16 v[114:117], v[228:231], v[180:183], v[114:117]
	v_mfma_f32_16x16x32_bf16 v[110:113], v[212:215], v[184:187], v[110:113]
	v_mfma_f32_16x16x32_bf16 v[106:109], v[218:221], v[184:187], v[106:109]
	v_mfma_f32_16x16x32_bf16 v[102:105], v[224:227], v[184:187], v[102:105]
	v_mfma_f32_16x16x32_bf16 v[98:101], v[228:231], v[184:187], v[98:101]
	v_mfma_f32_16x16x32_bf16 v[94:97], v[212:215], v[188:191], v[94:97]
	v_mfma_f32_16x16x32_bf16 v[90:93], v[218:221], v[188:191], v[90:93]
	v_mfma_f32_16x16x32_bf16 v[86:89], v[224:227], v[188:191], v[86:89]
	v_mfma_f32_16x16x32_bf16 v[82:85], v[228:231], v[188:191], v[82:85]
	v_mfma_f32_16x16x32_bf16 v[78:81], v[212:215], v[192:195], v[78:81]
	v_mfma_f32_16x16x32_bf16 v[74:77], v[218:221], v[192:195], v[74:77]
	v_mfma_f32_16x16x32_bf16 v[70:73], v[224:227], v[192:195], v[70:73]
	v_mfma_f32_16x16x32_bf16 v[66:69], v[228:231], v[192:195], v[66:69]
	ds_read_b128 v[180:183], v216
	ds_read_b128 v[184:187], v216 offset:2048
	ds_read_b128 v[188:191], v216 offset:4096
	ds_read_b128 v[192:195], v216 offset:6144
	ds_read_b128 v[232:235], v217
	ds_read_b128 v[236:239], v217 offset:2048
	ds_read_b128 v[240:243], v217 offset:4096
	ds_read_b128 v[244:247], v217 offset:6144
	s_waitcnt lgkmcnt(8)
	v_mfma_f32_16x16x32_bf16 v[62:65], v[212:215], v[196:199], v[62:65]
	v_mfma_f32_16x16x32_bf16 v[58:61], v[218:221], v[196:199], v[58:61]
	v_mfma_f32_16x16x32_bf16 v[54:57], v[224:227], v[196:199], v[54:57]
	v_mfma_f32_16x16x32_bf16 v[50:53], v[228:231], v[196:199], v[50:53]
	v_mfma_f32_16x16x32_bf16 v[46:49], v[212:215], v[200:203], v[46:49]
	v_mfma_f32_16x16x32_bf16 v[42:45], v[218:221], v[200:203], v[42:45]
	v_mfma_f32_16x16x32_bf16 v[38:41], v[224:227], v[200:203], v[38:41]
	v_mfma_f32_16x16x32_bf16 v[34:37], v[228:231], v[200:203], v[34:37]
	v_mfma_f32_16x16x32_bf16 v[30:33], v[212:215], v[204:207], v[30:33]
	v_mfma_f32_16x16x32_bf16 v[26:29], v[218:221], v[204:207], v[26:29]
	v_mfma_f32_16x16x32_bf16 v[22:25], v[224:227], v[204:207], v[22:25]
	v_mfma_f32_16x16x32_bf16 v[18:21], v[228:231], v[204:207], v[18:21]
	v_mfma_f32_16x16x32_bf16 v[14:17], v[212:215], v[208:211], v[14:17]
	v_mfma_f32_16x16x32_bf16 v[10:13], v[218:221], v[208:211], v[10:13]
	v_mfma_f32_16x16x32_bf16 v[6:9], v[224:227], v[208:211], v[6:9]
	v_mfma_f32_16x16x32_bf16 v[2:5], v[228:231], v[208:211], v[2:5]
	ds_read_b128 v[196:199], v216 offset:8192
	ds_read_b128 v[200:203], v216 offset:10240
	ds_read_b128 v[204:207], v216 offset:12288
	ds_read_b128 v[208:211], v216 offset:14336
	s_waitcnt lgkmcnt(4)
	v_mfma_f32_16x16x32_bf16 v[126:129], v[232:235], v[180:183], v[126:129]
	v_mfma_f32_16x16x32_bf16 v[122:125], v[236:239], v[180:183], v[122:125]
	v_mfma_f32_16x16x32_bf16 v[118:121], v[240:243], v[180:183], v[118:121]
	v_mfma_f32_16x16x32_bf16 v[114:117], v[244:247], v[180:183], v[114:117]
	v_mfma_f32_16x16x32_bf16 v[110:113], v[232:235], v[184:187], v[110:113]
	v_mfma_f32_16x16x32_bf16 v[106:109], v[236:239], v[184:187], v[106:109]
	v_mfma_f32_16x16x32_bf16 v[102:105], v[240:243], v[184:187], v[102:105]
	v_mfma_f32_16x16x32_bf16 v[98:101], v[244:247], v[184:187], v[98:101]
	v_mfma_f32_16x16x32_bf16 v[94:97], v[232:235], v[188:191], v[94:97]
	v_mfma_f32_16x16x32_bf16 v[90:93], v[236:239], v[188:191], v[90:93]
	v_mfma_f32_16x16x32_bf16 v[86:89], v[240:243], v[188:191], v[86:89]
	v_mfma_f32_16x16x32_bf16 v[82:85], v[244:247], v[188:191], v[82:85]
	v_mfma_f32_16x16x32_bf16 v[78:81], v[232:235], v[192:195], v[78:81]
	v_mfma_f32_16x16x32_bf16 v[74:77], v[236:239], v[192:195], v[74:77]
	v_mfma_f32_16x16x32_bf16 v[70:73], v[240:243], v[192:195], v[70:73]
	v_mfma_f32_16x16x32_bf16 v[66:69], v[244:247], v[192:195], v[66:69]
	s_waitcnt vmcnt(0)
	s_waitcnt lgkmcnt(0)
	s_barrier
	s_add_u32 s8, s8, 0x80
	s_addc_u32 s9, s9, 0
	s_add_u32 s98, s98, 0x80
	s_addc_u32 s99, s99, 0
	s_add_u32 s100, s100, 0x80
	s_addc_u32 s101, s101, 0
	s_cmpk_eq_i32 s8, 0x1580
	s_cbranch_scc1 .Lg2_p7_tail
	ds_read_b128 v[180:183], v148 offset:32768
	ds_read_b128 v[184:187], v148 offset:34816
	ds_read_b128 v[188:191], v148 offset:36864
	ds_read_b128 v[192:195], v148 offset:38912
	ds_read_b128 v[212:215], v149 offset:32768
	ds_read_b128 v[218:221], v149 offset:34816
	ds_read_b128 v[224:227], v149 offset:36864
	ds_read_b128 v[228:231], v149 offset:38912
	v_mfma_f32_16x16x32_bf16 v[62:65], v[232:235], v[196:199], v[62:65]
	s_mov_b32 m0, s96
	v_mfma_f32_16x16x32_bf16 v[58:61], v[236:239], v[196:199], v[58:61]
	global_load_lds_dwordx4 v140, s[98:99]
	v_mfma_f32_16x16x32_bf16 v[54:57], v[240:243], v[196:199], v[54:57]
	s_add_u32 m0, m0, 0x2000
	v_mfma_f32_16x16x32_bf16 v[50:53], v[244:247], v[196:199], v[50:53]
	global_load_lds_dwordx4 v152, s[98:99]
	v_mfma_f32_16x16x32_bf16 v[46:49], v[232:235], v[200:203], v[46:49]
	s_add_u32 m0, m0, 0x2000
	v_mfma_f32_16x16x32_bf16 v[42:45], v[236:239], v[200:203], v[42:45]
	global_load_lds_dwordx4 v156, s[98:99]
	v_mfma_f32_16x16x32_bf16 v[38:41], v[240:243], v[200:203], v[38:41]
	s_add_u32 m0, m0, 0x2000
	v_mfma_f32_16x16x32_bf16 v[34:37], v[244:247], v[200:203], v[34:37]
	global_load_lds_dwordx4 v160, s[98:99]
	v_mfma_f32_16x16x32_bf16 v[30:33], v[232:235], v[204:207], v[30:33]
	s_add_u32 m0, m0, 0xa000
	v_mfma_f32_16x16x32_bf16 v[26:29], v[236:239], v[204:207], v[26:29]
	global_load_lds_dwordx4 v164, s[100:101]
	v_mfma_f32_16x16x32_bf16 v[22:25], v[240:243], v[204:207], v[22:25]
	s_add_u32 m0, m0, 0x2000
	v_mfma_f32_16x16x32_bf16 v[18:21], v[244:247], v[204:207], v[18:21]
	global_load_lds_dwordx4 v168, s[100:101]
	v_mfma_f32_16x16x32_bf16 v[14:17], v[232:235], v[208:211], v[14:17]
	s_add_u32 m0, m0, 0x2000
	v_mfma_f32_16x16x32_bf16 v[10:13], v[236:239], v[208:211], v[10:13]
	global_load_lds_dwordx4 v172, s[100:101]
	v_mfma_f32_16x16x32_bf16 v[6:9], v[240:243], v[208:211], v[6:9]
	s_add_u32 m0, m0, 0x2000
	v_mfma_f32_16x16x32_bf16 v[2:5], v[244:247], v[208:211], v[2:5]
	global_load_lds_dwordx4 v176, s[100:101]
	ds_read_b128 v[196:199], v148 offset:40960
	ds_read_b128 v[200:203], v148 offset:43008
	ds_read_b128 v[204:207], v148 offset:45056
	ds_read_b128 v[208:211], v148 offset:47104
	s_waitcnt lgkmcnt(4)
	v_mfma_f32_16x16x32_bf16 v[126:129], v[212:215], v[180:183], v[126:129]
	v_mfma_f32_16x16x32_bf16 v[122:125], v[218:221], v[180:183], v[122:125]
	v_mfma_f32_16x16x32_bf16 v[118:121], v[224:227], v[180:183], v[118:121]
	v_mfma_f32_16x16x32_bf16 v[114:117], v[228:231], v[180:183], v[114:117]
	v_mfma_f32_16x16x32_bf16 v[110:113], v[212:215], v[184:187], v[110:113]
	v_mfma_f32_16x16x32_bf16 v[106:109], v[218:221], v[184:187], v[106:109]
	v_mfma_f32_16x16x32_bf16 v[102:105], v[224:227], v[184:187], v[102:105]
	v_mfma_f32_16x16x32_bf16 v[98:101], v[228:231], v[184:187], v[98:101]
	v_mfma_f32_16x16x32_bf16 v[94:97], v[212:215], v[188:191], v[94:97]
	v_mfma_f32_16x16x32_bf16 v[90:93], v[218:221], v[188:191], v[90:93]
	v_mfma_f32_16x16x32_bf16 v[86:89], v[224:227], v[188:191], v[86:89]
	v_mfma_f32_16x16x32_bf16 v[82:85], v[228:231], v[188:191], v[82:85]
	v_mfma_f32_16x16x32_bf16 v[78:81], v[212:215], v[192:195], v[78:81]
	v_mfma_f32_16x16x32_bf16 v[74:77], v[218:221], v[192:195], v[74:77]
	v_mfma_f32_16x16x32_bf16 v[70:73], v[224:227], v[192:195], v[70:73]
	v_mfma_f32_16x16x32_bf16 v[66:69], v[228:231], v[192:195], v[66:69]
	ds_read_b128 v[180:183], v216 offset:32768
	ds_read_b128 v[184:187], v216 offset:34816
	ds_read_b128 v[188:191], v216 offset:36864
	ds_read_b128 v[192:195], v216 offset:38912
	ds_read_b128 v[232:235], v217 offset:32768
	ds_read_b128 v[236:239], v217 offset:34816
	ds_read_b128 v[240:243], v217 offset:36864
	ds_read_b128 v[244:247], v217 offset:38912
	s_waitcnt lgkmcnt(8)
	v_mfma_f32_16x16x32_bf16 v[62:65], v[212:215], v[196:199], v[62:65]
	v_mfma_f32_16x16x32_bf16 v[58:61], v[218:221], v[196:199], v[58:61]
	v_mfma_f32_16x16x32_bf16 v[54:57], v[224:227], v[196:199], v[54:57]
	v_mfma_f32_16x16x32_bf16 v[50:53], v[228:231], v[196:199], v[50:53]
	v_mfma_f32_16x16x32_bf16 v[46:49], v[212:215], v[200:203], v[46:49]
	v_mfma_f32_16x16x32_bf16 v[42:45], v[218:221], v[200:203], v[42:45]
	v_mfma_f32_16x16x32_bf16 v[38:41], v[224:227], v[200:203], v[38:41]
	v_mfma_f32_16x16x32_bf16 v[34:37], v[228:231], v[200:203], v[34:37]
	v_mfma_f32_16x16x32_bf16 v[30:33], v[212:215], v[204:207], v[30:33]
	v_mfma_f32_16x16x32_bf16 v[26:29], v[218:221], v[204:207], v[26:29]
	v_mfma_f32_16x16x32_bf16 v[22:25], v[224:227], v[204:207], v[22:25]
	v_mfma_f32_16x16x32_bf16 v[18:21], v[228:231], v[204:207], v[18:21]
	v_mfma_f32_16x16x32_bf16 v[14:17], v[212:215], v[208:211], v[14:17]
	v_mfma_f32_16x16x32_bf16 v[10:13], v[218:221], v[208:211], v[10:13]
	v_mfma_f32_16x16x32_bf16 v[6:9], v[224:227], v[208:211], v[6:9]
	v_mfma_f32_16x16x32_bf16 v[2:5], v[228:231], v[208:211], v[2:5]
	ds_read_b128 v[196:199], v216 offset:40960
	ds_read_b128 v[200:203], v216 offset:43008
	ds_read_b128 v[204:207], v216 offset:45056
	ds_read_b128 v[208:211], v216 offset:47104
	s_waitcnt lgkmcnt(4)
	v_mfma_f32_16x16x32_bf16 v[126:129], v[232:235], v[180:183], v[126:129]
	v_mfma_f32_16x16x32_bf16 v[122:125], v[236:239], v[180:183], v[122:125]
	v_mfma_f32_16x16x32_bf16 v[118:121], v[240:243], v[180:183], v[118:121]
	v_mfma_f32_16x16x32_bf16 v[114:117], v[244:247], v[180:183], v[114:117]
	v_mfma_f32_16x16x32_bf16 v[110:113], v[232:235], v[184:187], v[110:113]
	v_mfma_f32_16x16x32_bf16 v[106:109], v[236:239], v[184:187], v[106:109]
	v_mfma_f32_16x16x32_bf16 v[102:105], v[240:243], v[184:187], v[102:105]
	v_mfma_f32_16x16x32_bf16 v[98:101], v[244:247], v[184:187], v[98:101]
	v_mfma_f32_16x16x32_bf16 v[94:97], v[232:235], v[188:191], v[94:97]
	v_mfma_f32_16x16x32_bf16 v[90:93], v[236:239], v[188:191], v[90:93]
	v_mfma_f32_16x16x32_bf16 v[86:89], v[240:243], v[188:191], v[86:89]
	v_mfma_f32_16x16x32_bf16 v[82:85], v[244:247], v[188:191], v[82:85]
	v_mfma_f32_16x16x32_bf16 v[78:81], v[232:235], v[192:195], v[78:81]
	v_mfma_f32_16x16x32_bf16 v[74:77], v[236:239], v[192:195], v[74:77]
	v_mfma_f32_16x16x32_bf16 v[70:73], v[240:243], v[192:195], v[70:73]
	v_mfma_f32_16x16x32_bf16 v[66:69], v[244:247], v[192:195], v[66:69]
	s_waitcnt vmcnt(0)
	s_waitcnt lgkmcnt(0)
	s_barrier
	s_add_u32 s8, s8, 0x80
	s_addc_u32 s9, s9, 0
	s_add_u32 s98, s98, 0x80
	s_addc_u32 s99, s99, 0
	s_add_u32 s100, s100, 0x80
	s_addc_u32 s101, s101, 0
	s_cmpk_eq_i32 s8, 0x1580
	s_cbranch_scc1 .Lg2_p7_tail
	ds_read_b128 v[180:183], v148
	ds_read_b128 v[184:187], v148 offset:2048
	ds_read_b128 v[188:191], v148 offset:4096
	ds_read_b128 v[192:195], v148 offset:6144
	ds_read_b128 v[212:215], v149
	ds_read_b128 v[218:221], v149 offset:2048
	ds_read_b128 v[224:227], v149 offset:4096
	ds_read_b128 v[228:231], v149 offset:6144
	v_mfma_f32_16x16x32_bf16 v[62:65], v[232:235], v[196:199], v[62:65]
	s_add_u32 m0, s96, 0x8000
	v_mfma_f32_16x16x32_bf16 v[58:61], v[236:239], v[196:199], v[58:61]
	global_load_lds_dwordx4 v140, s[98:99]
	v_mfma_f32_16x16x32_bf16 v[54:57], v[240:243], v[196:199], v[54:57]
	s_add_u32 m0, m0, 0x2000
	v_mfma_f32_16x16x32_bf16 v[50:53], v[244:247], v[196:199], v[50:53]
	global_load_lds_dwordx4 v152, s[98:99]
	v_mfma_f32_16x16x32_bf16 v[46:49], v[232:235], v[200:203], v[46:49]
	s_add_u32 m0, m0, 0x2000
	v_mfma_f32_16x16x32_bf16 v[42:45], v[236:239], v[200:203], v[42:45]
	global_load_lds_dwordx4 v156, s[98:99]
	v_mfma_f32_16x16x32_bf16 v[38:41], v[240:243], v[200:203], v[38:41]
	s_add_u32 m0, m0, 0x2000
	v_mfma_f32_16x16x32_bf16 v[34:37], v[244:247], v[200:203], v[34:37]
	global_load_lds_dwordx4 v160, s[98:99]
	v_mfma_f32_16x16x32_bf16 v[30:33], v[232:235], v[204:207], v[30:33]
	s_add_u32 m0, m0, 0xa000
	v_mfma_f32_16x16x32_bf16 v[26:29], v[236:239], v[204:207], v[26:29]
	global_load_lds_dwordx4 v164, s[100:101]
	v_mfma_f32_16x16x32_bf16 v[22:25], v[240:243], v[204:207], v[22:25]
	s_add_u32 m0, m0, 0x2000
	v_mfma_f32_16x16x32_bf16 v[18:21], v[244:247], v[204:207], v[18:21]
	global_load_lds_dwordx4 v168, s[100:101]
	v_mfma_f32_16x16x32_bf16 v[14:17], v[232:235], v[208:211], v[14:17]
	s_add_u32 m0, m0, 0x2000
	v_mfma_f32_16x16x32_bf16 v[10:13], v[236:239], v[208:211], v[10:13]
	global_load_lds_dwordx4 v172, s[100:101]
	v_mfma_f32_16x16x32_bf16 v[6:9], v[240:243], v[208:211], v[6:9]
	s_add_u32 m0, m0, 0x2000
	v_mfma_f32_16x16x32_bf16 v[2:5], v[244:247], v[208:211], v[2:5]
	global_load_lds_dwordx4 v176, s[100:101]
	s_branch .Lg2_p7_loop

.LBB0_645:
	s_lshl_b32 s36, s28, 8
	v_or_b32_e32 v2, s36, v1
	v_ashrrev_i32_e32 v3, 31, v2
	v_lshlrev_b64 v[62:63], 11, v[2:3]
	v_lshl_add_u64 v[2:3], v[130:131], 0, v[62:63]
	v_add_co_u32_e32 v6, vcc, 0x20000, v2
	s_lshl_b32 s29, s27, 8
	s_nop 0
	v_addc_co_u32_e32 v7, vcc, 0, v3, vcc
	v_or_b32_e32 v4, s29, v1
	global_load_dwordx4 v[30:33], v[2:3], off
	global_load_dwordx4 v[34:37], v[6:7], off
	v_add_co_u32_e32 v6, vcc, 0x40000, v2
	v_ashrrev_i32_e32 v5, 31, v4
	s_nop 0
	v_addc_co_u32_e32 v7, vcc, 0, v3, vcc
	v_lshlrev_b64 v[64:65], 11, v[4:5]
	v_add_co_u32_e32 v2, vcc, 0x60000, v2
	v_lshl_add_u64 v[4:5], v[132:133], 0, v[64:65]
	s_nop 0
	v_addc_co_u32_e32 v3, vcc, 0, v3, vcc
	global_load_dwordx4 v[38:41], v[6:7], off
	global_load_dwordx4 v[42:45], v[2:3], off
	v_add_co_u32_e32 v2, vcc, s12, v4
	s_waitcnt vmcnt(63) expcnt(7) lgkmcnt(15)
	s_nop 0
	v_addc_co_u32_e32 v3, vcc, 0, v5, vcc
	s_barrier
	global_load_dwordx4 v[46:49], v[4:5], off
	global_load_dwordx4 v[50:53], v[2:3], off
	v_add_co_u32_e32 v2, vcc, s13, v4
	s_mov_b32 s37, 0
	s_nop 0
	v_addc_co_u32_e32 v3, vcc, 0, v5, vcc
	v_add_co_u32_e32 v4, vcc, s14, v4
	s_mov_b64 s[8:9], 0
	s_nop 0
	v_addc_co_u32_e32 v5, vcc, 0, v5, vcc
	global_load_dwordx4 v[54:57], v[2:3], off
	global_load_dwordx4 v[58:61], v[4:5], off
	v_mov_b32_e32 v2, 0
	v_mov_b32_e32 v3, v2
	v_mov_b32_e32 v4, v2
	v_mov_b32_e32 v5, v2
	v_mov_b32_e32 v6, v2
	v_mov_b32_e32 v7, v2
	v_mov_b32_e32 v8, v2
	v_mov_b32_e32 v9, v2
	v_mov_b32_e32 v10, v2
	v_mov_b32_e32 v11, v2
	v_mov_b32_e32 v12, v2
	v_mov_b32_e32 v13, v2
	v_mov_b32_e32 v14, v2
	v_mov_b32_e32 v15, v2
	v_mov_b32_e32 v16, v2
	v_mov_b32_e32 v17, v2
	v_mov_b32_e32 v18, v2
	v_mov_b32_e32 v19, v2
	v_mov_b32_e32 v20, v2
	v_mov_b32_e32 v21, v2
	v_mov_b32_e32 v22, v2
	v_mov_b32_e32 v23, v2
	v_mov_b32_e32 v24, v2
	v_mov_b32_e32 v25, v2
	v_mov_b32_e32 v26, v2
	v_mov_b32_e32 v27, v2
	v_mov_b32_e32 v28, v2
	v_lshl_add_u64 v[136:137], v[134:135], 0, v[62:63]
	v_lshl_add_u64 v[138:139], v[134:135], 0, v[64:65]
	v_mov_b32_e32 v29, v2
	v_mov_b32_e32 v62, v2
	v_mov_b32_e32 v63, v2
	v_mov_b32_e32 v64, v2
	v_mov_b32_e32 v65, v2
	v_mov_b32_e32 v66, v2
	v_mov_b32_e32 v67, v2
	v_mov_b32_e32 v68, v2
	v_mov_b32_e32 v69, v2
	v_mov_b32_e32 v70, v2
	v_mov_b32_e32 v71, v2
	v_mov_b32_e32 v72, v2
	v_mov_b32_e32 v73, v2
	v_mov_b32_e32 v74, v2
	v_mov_b32_e32 v75, v2
	v_mov_b32_e32 v76, v2
	v_mov_b32_e32 v77, v2
	v_mov_b32_e32 v78, v2
	v_mov_b32_e32 v79, v2
	v_mov_b32_e32 v80, v2
	v_mov_b32_e32 v81, v2
	v_mov_b32_e32 v82, v2
	v_mov_b32_e32 v83, v2
	v_mov_b32_e32 v84, v2
	s_waitcnt vmcnt(7)
	ds_write_b128 v146, v[30:33]
	s_waitcnt vmcnt(6)
	ds_write_b128 v146, v[34:37] offset:8192
	s_waitcnt vmcnt(5)
	ds_write_b128 v146, v[38:41] offset:16384
	s_waitcnt vmcnt(4)
	ds_write_b128 v146, v[42:45] offset:24576
	s_waitcnt vmcnt(3)
	ds_write_b128 v147, v[46:49]
	s_waitcnt vmcnt(2)
	ds_write_b128 v147, v[50:53] offset:8192
	s_waitcnt vmcnt(1)
	ds_write_b128 v147, v[54:57] offset:16384
	s_waitcnt vmcnt(0)
	ds_write_b128 v147, v[58:61] offset:24576
	v_mov_b32_e32 v30, v2
	v_mov_b32_e32 v31, v2
	v_mov_b32_e32 v32, v2
	v_mov_b32_e32 v33, v2
	v_mov_b32_e32 v34, v2
	v_mov_b32_e32 v35, v2
	v_mov_b32_e32 v36, v2
	v_mov_b32_e32 v37, v2
	v_mov_b32_e32 v38, v2
	v_mov_b32_e32 v39, v2
	v_mov_b32_e32 v40, v2
	v_mov_b32_e32 v41, v2
	v_mov_b32_e32 v42, v2
	v_mov_b32_e32 v43, v2
	v_mov_b32_e32 v44, v2
	v_mov_b32_e32 v45, v2
	v_mov_b32_e32 v46, v2
	v_mov_b32_e32 v47, v2
	v_mov_b32_e32 v48, v2
	v_mov_b32_e32 v49, v2
	v_mov_b32_e32 v50, v2
	v_mov_b32_e32 v51, v2
	v_mov_b32_e32 v52, v2
	v_mov_b32_e32 v53, v2
	v_mov_b32_e32 v54, v2
	v_mov_b32_e32 v55, v2
	v_mov_b32_e32 v56, v2
	v_mov_b32_e32 v57, v2
	v_mov_b32_e32 v58, v2
	v_mov_b32_e32 v59, v2
	v_mov_b32_e32 v60, v2
	v_mov_b32_e32 v61, v2
	v_mov_b32_e32 v85, v2
	v_mov_b32_e32 v86, v2
	v_mov_b32_e32 v87, v2
	v_mov_b32_e32 v88, v2
	v_mov_b32_e32 v89, v2
	v_mov_b32_e32 v90, v2
	v_mov_b32_e32 v91, v2
	v_mov_b32_e32 v92, v2
	v_mov_b32_e32 v93, v2
	v_mov_b32_e32 v94, v2
	v_mov_b32_e32 v95, v2
	v_mov_b32_e32 v96, v2
	v_mov_b32_e32 v97, v2
	v_mov_b32_e32 v98, v2
	v_mov_b32_e32 v99, v2
	v_mov_b32_e32 v100, v2
	v_mov_b32_e32 v101, v2
	v_mov_b32_e32 v102, v2
	v_mov_b32_e32 v103, v2
	v_mov_b32_e32 v104, v2
	v_mov_b32_e32 v105, v2
	v_mov_b32_e32 v106, v2
	v_mov_b32_e32 v107, v2
	v_mov_b32_e32 v108, v2
	v_mov_b32_e32 v109, v2
	v_mov_b32_e32 v110, v2
	v_mov_b32_e32 v111, v2
	v_mov_b32_e32 v112, v2
	v_mov_b32_e32 v113, v2
	v_mov_b32_e32 v114, v2
	v_mov_b32_e32 v115, v2
	v_mov_b32_e32 v116, v2
	v_mov_b32_e32 v117, v2
	v_mov_b32_e32 v118, v2
	v_mov_b32_e32 v119, v2
	v_mov_b32_e32 v120, v2
	v_mov_b32_e32 v121, v2
	v_mov_b32_e32 v122, v2
	v_mov_b32_e32 v123, v2
	v_mov_b32_e32 v124, v2
	v_mov_b32_e32 v125, v2
	v_mov_b32_e32 v126, v2
	v_mov_b32_e32 v127, v2
	v_mov_b32_e32 v128, v2
	v_mov_b32_e32 v129, v2
	s_waitcnt lgkmcnt(0)
	s_barrier
	s_movk_i32 s97, 0x70
	v_readfirstlane_b32 s98, v136
	v_readfirstlane_b32 s99, v137
	v_subrev_u32_e32 v248, s98, v136
	v_bfi_b32 v248, s97, v146, v248
	v_add_u32_e32 v140, s15, v248
	v_add_u32_e32 v152, s16, v248
	v_add_u32_e32 v156, s17, v248
	v_add_u32_e32 v160, s18, v248
	s_add_u32 s98, s98, s8
	s_addc_u32 s99, s99, s9
	s_add_u32 s98, s98, 0x80
	s_addc_u32 s99, s99, 0
	v_readfirstlane_b32 s100, v138
	v_readfirstlane_b32 s101, v139
	v_subrev_u32_e32 v250, s100, v138
	v_bfi_b32 v250, s97, v146, v250
	v_add_u32_e32 v164, s19, v250
	v_add_u32_e32 v168, s20, v250
	v_add_u32_e32 v172, s21, v250
	v_add_u32_e32 v176, s22, v250
	s_add_u32 s100, s100, s8
	s_addc_u32 s101, s101, s9
	s_add_u32 s100, s100, 0x80
	s_addc_u32 s101, s101, 0
	v_readfirstlane_b32 s96, v146
	s_and_b32 s96, s96, 0xfc00
	s_add_u32 m0, s96, 0x8000
	s_nop 0
	global_load_lds_dwordx4 v140, s[98:99]
	s_add_u32 m0, m0, 0x2000
	s_nop 0
	global_load_lds_dwordx4 v152, s[98:99]
	s_add_u32 m0, m0, 0x2000
	s_nop 0
	global_load_lds_dwordx4 v156, s[98:99]
	s_add_u32 m0, m0, 0x2000
	s_nop 0
	global_load_lds_dwordx4 v160, s[98:99]
	s_add_u32 m0, m0, 0xa000
	s_nop 0
	global_load_lds_dwordx4 v164, s[100:101]
	s_add_u32 m0, m0, 0x2000
	s_nop 0
	global_load_lds_dwordx4 v168, s[100:101]
	s_add_u32 m0, m0, 0x2000
	s_nop 0
	global_load_lds_dwordx4 v172, s[100:101]
	s_add_u32 m0, m0, 0x2000
	s_nop 0
	global_load_lds_dwordx4 v176, s[100:101]
	ds_read_b128 v[180:183], v148
	ds_read_b128 v[184:187], v148 offset:2048
	ds_read_b128 v[188:191], v148 offset:4096
	ds_read_b128 v[192:195], v148 offset:6144
	ds_read_b128 v[212:215], v149
	ds_read_b128 v[218:221], v149 offset:2048
	ds_read_b128 v[224:227], v149 offset:4096
	ds_read_b128 v[228:231], v149 offset:6144

.LBB0_749:
	s_mul_hi_i32 s0, s3, 0x2e8ba2e9
	s_lshr_b32 s1, s0, 31
	s_ashr_i32 s0, s0, 4
	s_add_i32 s24, s0, s1
	s_mul_i32 s1, s24, 0xffffffa8
	s_add_i32 s1, s1, s3
	s_ashr_i32 s21, s1, 31
	s_lshl_b32 s0, s24, 2
	s_lshr_b32 s21, s21, 30
	s_add_i32 s21, s1, s21
	s_add_i32 s0, s6, s0
	s_ashr_i32 s22, s21, 2
	s_add_i32 s0, s0, s1
	s_lshl_b32 s25, s22, 10
	s_lshl_b32 s0, s0, 8
	s_sub_i32 s21, s0, s25
	v_or_b32_e32 v2, s21, v1
	v_ashrrev_i32_e32 v3, 31, v2
	v_lshlrev_b64 v[2:3], 11, v[2:3]
	v_lshl_add_u64 v[2:3], v[132:133], 0, v[2:3]
	v_add_co_u32_e32 v6, vcc, s9, v2
	s_lshl_b32 s22, s22, 8
	s_nop 0
	v_addc_co_u32_e32 v7, vcc, 0, v3, vcc
	v_or_b32_e32 v4, s22, v1
	global_load_dwordx4 v[20:23], v[2:3], off
	global_load_dwordx4 v[24:27], v[6:7], off
	v_add_co_u32_e32 v6, vcc, s10, v2
	v_ashrrev_i32_e32 v5, 31, v4
	s_nop 0
	v_addc_co_u32_e32 v7, vcc, 0, v3, vcc
	v_lshlrev_b64 v[52:53], 11, v[4:5]
	v_add_co_u32_e32 v2, vcc, s11, v2
	v_lshl_add_u64 v[4:5], v[134:135], 0, v[52:53]
	s_nop 0
	v_addc_co_u32_e32 v3, vcc, 0, v3, vcc
	global_load_dwordx4 v[28:31], v[6:7], off
	global_load_dwordx4 v[32:35], v[2:3], off
	v_add_co_u32_e32 v2, vcc, s9, v4
	s_waitcnt vmcnt(63) expcnt(7) lgkmcnt(15)
	s_nop 0
	v_addc_co_u32_e32 v3, vcc, 0, v5, vcc
	s_barrier
	global_load_dwordx4 v[36:39], v[4:5], off
	global_load_dwordx4 v[40:43], v[2:3], off
	v_add_co_u32_e32 v2, vcc, s10, v4
	s_mulk_i32 s24, 0x5400
	s_nop 0
	v_addc_co_u32_e32 v3, vcc, 0, v5, vcc
	v_add_co_u32_e32 v4, vcc, s11, v4
	v_subrev_u32_e32 v19, s25, v130
	s_nop 0
	v_addc_co_u32_e32 v5, vcc, 0, v5, vcc
	global_load_dwordx4 v[44:47], v[2:3], off
	global_load_dwordx4 v[48:51], v[4:5], off
	v_subrev_u32_e32 v54, s24, v19
	v_ashrrev_i32_e32 v55, 31, v54
	v_lshlrev_b64 v[54:55], 11, v[54:55]
	s_mov_b64 s[0:1], 0
	s_mov_b32 s23, 0
	v_mov_b32_e32 v2, 0
	v_mov_b32_e32 v3, v131
	v_mov_b32_e32 v4, v131
	v_mov_b32_e32 v5, v131
	v_mov_b32_e32 v6, 0
	v_mov_b32_e32 v7, v131
	v_mov_b32_e32 v8, v131
	v_mov_b32_e32 v9, v131
	v_mov_b32_e32 v10, 0
	v_mov_b32_e32 v11, v131
	v_mov_b32_e32 v12, v131
	v_mov_b32_e32 v13, v131
	v_mov_b32_e32 v14, 0
	v_mov_b32_e32 v15, v131
	v_mov_b32_e32 v16, v131
	v_mov_b32_e32 v17, v131
	v_mov_b32_e32 v18, 0
	v_lshl_add_u64 v[140:141], v[138:139], 0, v[52:53]
	v_lshl_add_u64 v[142:143], v[138:139], 0, v[54:55]
	v_mov_b32_e32 v19, v131
	v_mov_b32_e32 v52, v131
	v_mov_b32_e32 v53, v131
	v_mov_b32_e32 v54, 0
	v_mov_b32_e32 v55, v131
	v_mov_b32_e32 v56, v131
	v_mov_b32_e32 v57, v131
	v_mov_b32_e32 v58, 0
	v_mov_b32_e32 v59, v131
	v_mov_b32_e32 v60, v131
	v_mov_b32_e32 v61, v131
	v_mov_b32_e32 v62, 0
	v_mov_b32_e32 v63, v131
	v_mov_b32_e32 v64, v131
	v_mov_b32_e32 v65, v131
	v_mov_b32_e32 v66, 0
	v_mov_b32_e32 v67, v131
	v_mov_b32_e32 v68, v131
	v_mov_b32_e32 v69, v131
	v_mov_b32_e32 v70, 0
	v_mov_b32_e32 v71, v131
	v_mov_b32_e32 v72, v131
	v_mov_b32_e32 v73, v131
	v_mov_b32_e32 v74, 0
	s_waitcnt vmcnt(7)
	ds_write_b128 v144, v[20:23]
	s_waitcnt vmcnt(6)
	ds_write_b128 v144, v[24:27] offset:8192
	s_waitcnt vmcnt(5)
	ds_write_b128 v144, v[28:31] offset:16384
	s_waitcnt vmcnt(4)
	ds_write_b128 v144, v[32:35] offset:24576
	s_waitcnt vmcnt(3)
	ds_write_b128 v145, v[36:39]
	s_waitcnt vmcnt(2)
	ds_write_b128 v145, v[40:43] offset:8192
	s_waitcnt vmcnt(1)
	ds_write_b128 v145, v[44:47] offset:16384
	s_waitcnt vmcnt(0)
	ds_write_b128 v145, v[48:51] offset:24576
	v_mov_b32_e32 v20, v131
	v_mov_b32_e32 v21, v131
	v_mov_b32_e32 v22, 0
	v_mov_b32_e32 v23, v131
	v_mov_b32_e32 v24, v131
	v_mov_b32_e32 v25, v131
	v_mov_b32_e32 v26, 0
	v_mov_b32_e32 v27, v131
	v_mov_b32_e32 v28, v131
	v_mov_b32_e32 v29, v131
	v_mov_b32_e32 v30, 0
	v_mov_b32_e32 v31, v131
	v_mov_b32_e32 v32, v131
	v_mov_b32_e32 v33, v131
	v_mov_b32_e32 v34, 0
	v_mov_b32_e32 v35, v131
	v_mov_b32_e32 v36, v131
	v_mov_b32_e32 v37, v131
	v_mov_b32_e32 v38, 0
	v_mov_b32_e32 v39, v131
	v_mov_b32_e32 v40, v131
	v_mov_b32_e32 v41, v131
	v_mov_b32_e32 v42, 0
	v_mov_b32_e32 v43, v131
	v_mov_b32_e32 v44, v131
	v_mov_b32_e32 v45, v131
	v_mov_b32_e32 v46, 0
	v_mov_b32_e32 v47, v131
	v_mov_b32_e32 v48, v131
	v_mov_b32_e32 v49, v131
	v_mov_b32_e32 v50, 0
	v_mov_b32_e32 v51, v131
	v_mov_b32_e32 v75, v131
	v_mov_b32_e32 v76, v131
	v_mov_b32_e32 v77, v131
	v_mov_b32_e32 v78, 0
	v_mov_b32_e32 v79, v131
	v_mov_b32_e32 v80, v131
	v_mov_b32_e32 v81, v131
	v_mov_b32_e32 v82, 0
	v_mov_b32_e32 v83, v131
	v_mov_b32_e32 v84, v131
	v_mov_b32_e32 v85, v131
	v_mov_b32_e32 v86, 0
	v_mov_b32_e32 v87, v131
	v_mov_b32_e32 v88, v131
	v_mov_b32_e32 v89, v131
	v_mov_b32_e32 v90, 0
	v_mov_b32_e32 v91, v131
	v_mov_b32_e32 v92, v131
	v_mov_b32_e32 v93, v131
	v_mov_b32_e32 v94, 0
	v_mov_b32_e32 v95, v131
	v_mov_b32_e32 v96, v131
	v_mov_b32_e32 v97, v131
	v_mov_b32_e32 v98, 0
	v_mov_b32_e32 v99, v131
	v_mov_b32_e32 v100, v131
	v_mov_b32_e32 v101, v131
	v_mov_b32_e32 v102, 0
	v_mov_b32_e32 v103, v131
	v_mov_b32_e32 v104, v131
	v_mov_b32_e32 v105, v131
	v_mov_b32_e32 v106, 0
	v_mov_b32_e32 v107, v131
	v_mov_b32_e32 v108, v131
	v_mov_b32_e32 v109, v131
	v_mov_b32_e32 v110, 0
	v_mov_b32_e32 v111, v131
	v_mov_b32_e32 v112, v131
	v_mov_b32_e32 v113, v131
	v_mov_b32_e32 v114, 0
	v_mov_b32_e32 v115, v131
	v_mov_b32_e32 v116, v131
	v_mov_b32_e32 v117, v131
	v_mov_b32_e32 v118, 0
	v_mov_b32_e32 v119, v131
	v_mov_b32_e32 v120, v131
	v_mov_b32_e32 v121, v131
	v_mov_b32_e32 v122, 0
	v_mov_b32_e32 v123, v131
	v_mov_b32_e32 v124, v131
	v_mov_b32_e32 v125, v131
	v_mov_b32_e32 v126, 0
	v_mov_b32_e32 v127, v131
	v_mov_b32_e32 v128, v131
	v_mov_b32_e32 v129, v131
	s_waitcnt lgkmcnt(0)
	s_barrier
	s_movk_i32 s97, 0x70
	v_readfirstlane_b32 s98, v142
	v_readfirstlane_b32 s99, v143
	v_subrev_u32_e32 v215, s98, v142
	v_bfi_b32 v215, s97, v144, v215
	v_add_u32_e32 v150, s12, v215
	v_add_u32_e32 v154, s13, v215
	v_add_u32_e32 v158, s14, v215
	v_add_u32_e32 v162, s15, v215
	s_add_u32 s98, s98, s0
	s_addc_u32 s99, s99, s1
	s_add_u32 s98, s98, 0x80
	s_addc_u32 s99, s99, 0
	v_readfirstlane_b32 s100, v140
	v_readfirstlane_b32 s101, v141
	v_subrev_u32_e32 v252, s100, v140
	v_bfi_b32 v252, s97, v144, v252
	v_add_u32_e32 v166, s16, v252
	v_add_u32_e32 v170, s17, v252
	v_add_u32_e32 v174, s18, v252
	v_add_u32_e32 v178, s19, v252
	s_add_u32 s100, s100, s0
	s_addc_u32 s101, s101, s1
	s_add_u32 s100, s100, 0x80
	s_addc_u32 s101, s101, 0
	v_readfirstlane_b32 s96, v144
	s_and_b32 s96, s96, 0xfc00
	s_add_u32 m0, s96, 0x8000
	s_nop 0
	global_load_lds_dwordx4 v150, s[98:99]
	s_add_u32 m0, m0, 0x2000
	s_nop 0
	global_load_lds_dwordx4 v154, s[98:99]
	s_add_u32 m0, m0, 0x2000
	s_nop 0
	global_load_lds_dwordx4 v158, s[98:99]
	s_add_u32 m0, m0, 0x2000
	s_nop 0
	global_load_lds_dwordx4 v162, s[98:99]
	s_add_u32 m0, m0, 0xa000
	s_nop 0
	global_load_lds_dwordx4 v166, s[100:101]
	s_add_u32 m0, m0, 0x2000
	s_nop 0
	global_load_lds_dwordx4 v170, s[100:101]
	s_add_u32 m0, m0, 0x2000
	s_nop 0
	global_load_lds_dwordx4 v174, s[100:101]
	s_add_u32 m0, m0, 0x2000
	s_nop 0
	global_load_lds_dwordx4 v178, s[100:101]
	ds_read_b128 v[182:185], v146
	ds_read_b128 v[186:189], v146 offset:2048
	ds_read_b128 v[190:193], v146 offset:4096
	ds_read_b128 v[194:197], v146 offset:6144
	ds_read_b128 v[218:221], v147
	ds_read_b128 v[224:227], v147 offset:2048
	ds_read_b128 v[228:231], v147 offset:4096
	ds_read_b128 v[232:235], v147 offset:6144

.LBB0_773:
	s_lshl_b32 s37, s29, 8
	v_or_b32_e32 v27, s37, v1
	v_mad_i64_i32 v[2:3], s[8:9], v27, s12, v[130:131]
	v_add_co_u32_e32 v6, vcc, 0x58000, v2
	s_lshl_b32 s36, s28, 8
	s_nop 0
	v_addc_co_u32_e32 v7, vcc, 0, v3, vcc
	global_load_dwordx4 v[28:31], v[2:3], off
	global_load_dwordx4 v[32:35], v[6:7], off
	v_add_co_u32_e32 v6, vcc, 0xb0000, v2
	v_or_b32_e32 v60, s36, v1
	s_nop 0
	v_addc_co_u32_e32 v7, vcc, 0, v3, vcc
	v_add_co_u32_e32 v2, vcc, 0x108000, v2
	v_mad_i64_i32 v[4:5], s[8:9], v60, s12, v[132:133]
	s_nop 0
	v_addc_co_u32_e32 v3, vcc, 0, v3, vcc
	global_load_dwordx4 v[36:39], v[6:7], off
	global_load_dwordx4 v[40:43], v[2:3], off
	v_add_co_u32_e32 v2, vcc, s13, v4
	s_waitcnt vmcnt(63) expcnt(7) lgkmcnt(15)
	s_nop 0
	v_addc_co_u32_e32 v3, vcc, 0, v5, vcc
	s_barrier
	global_load_dwordx4 v[44:47], v[4:5], off
	global_load_dwordx4 v[48:51], v[2:3], off
	v_add_co_u32_e32 v2, vcc, s14, v4
	s_mov_b32 s38, 0
	s_nop 0
	v_addc_co_u32_e32 v3, vcc, 0, v5, vcc
	v_add_co_u32_e32 v4, vcc, s15, v4
	s_mov_b64 s[8:9], 0
	s_nop 0
	v_addc_co_u32_e32 v5, vcc, 0, v5, vcc
	global_load_dwordx4 v[52:55], v[2:3], off
	global_load_dwordx4 v[56:59], v[4:5], off
	v_mov_b32_e32 v2, 0
	v_mov_b32_e32 v3, v2
	v_mov_b32_e32 v4, v2
	v_mov_b32_e32 v5, v2
	v_mov_b32_e32 v6, v2
	v_mov_b32_e32 v7, v2
	v_mov_b32_e32 v8, v2
	v_mov_b32_e32 v9, v2
	v_mov_b32_e32 v10, v2
	v_mov_b32_e32 v11, v2
	v_mov_b32_e32 v12, v2
	v_mov_b32_e32 v13, v2
	v_mov_b32_e32 v14, v2
	v_mov_b32_e32 v15, v2
	v_mov_b32_e32 v16, v2
	v_mov_b32_e32 v17, v2
	v_mov_b32_e32 v18, v2
	v_mov_b32_e32 v19, v2
	v_mov_b32_e32 v20, v2
	v_mov_b32_e32 v21, v2
	v_mov_b32_e32 v22, v2
	v_mov_b32_e32 v23, v2
	v_mov_b32_e32 v24, v2
	v_mov_b32_e32 v25, v2
	v_mov_b32_e32 v26, v2
	v_mad_i64_i32 v[136:137], s[40:41], v27, s12, v[134:135]
	v_mad_i64_i32 v[138:139], s[40:41], v60, s12, v[134:135]
	v_mov_b32_e32 v27, v2
	v_mov_b32_e32 v60, v2
	v_mov_b32_e32 v61, v2
	v_mov_b32_e32 v62, v2
	v_mov_b32_e32 v63, v2
	v_mov_b32_e32 v64, v2
	v_mov_b32_e32 v65, v2
	v_mov_b32_e32 v66, v2
	v_mov_b32_e32 v67, v2
	v_mov_b32_e32 v68, v2
	v_mov_b32_e32 v69, v2
	v_mov_b32_e32 v70, v2
	v_mov_b32_e32 v71, v2
	v_mov_b32_e32 v72, v2
	v_mov_b32_e32 v73, v2
	v_mov_b32_e32 v74, v2
	v_mov_b32_e32 v75, v2
	v_mov_b32_e32 v76, v2
	v_mov_b32_e32 v77, v2
	v_mov_b32_e32 v78, v2
	v_mov_b32_e32 v79, v2
	v_mov_b32_e32 v80, v2
	v_mov_b32_e32 v81, v2
	v_mov_b32_e32 v82, v2
	s_waitcnt vmcnt(7)
	ds_write_b128 v146, v[28:31]
	s_waitcnt vmcnt(6)
	ds_write_b128 v146, v[32:35] offset:8192
	s_waitcnt vmcnt(5)
	ds_write_b128 v146, v[36:39] offset:16384
	s_waitcnt vmcnt(4)
	ds_write_b128 v146, v[40:43] offset:24576
	s_waitcnt vmcnt(3)
	ds_write_b128 v147, v[44:47]
	s_waitcnt vmcnt(2)
	ds_write_b128 v147, v[48:51] offset:8192
	s_waitcnt vmcnt(1)
	ds_write_b128 v147, v[52:55] offset:16384
	s_waitcnt vmcnt(0)
	ds_write_b128 v147, v[56:59] offset:24576
	v_mov_b32_e32 v28, v2
	v_mov_b32_e32 v29, v2
	v_mov_b32_e32 v30, v2
	v_mov_b32_e32 v31, v2
	v_mov_b32_e32 v32, v2
	v_mov_b32_e32 v33, v2
	v_mov_b32_e32 v34, v2
	v_mov_b32_e32 v35, v2
	v_mov_b32_e32 v36, v2
	v_mov_b32_e32 v37, v2
	v_mov_b32_e32 v38, v2
	v_mov_b32_e32 v39, v2
	v_mov_b32_e32 v40, v2
	v_mov_b32_e32 v41, v2
	v_mov_b32_e32 v42, v2
	v_mov_b32_e32 v43, v2
	v_mov_b32_e32 v44, v2
	v_mov_b32_e32 v45, v2
	v_mov_b32_e32 v46, v2
	v_mov_b32_e32 v47, v2
	v_mov_b32_e32 v48, v2
	v_mov_b32_e32 v49, v2
	v_mov_b32_e32 v50, v2
	v_mov_b32_e32 v51, v2
	v_mov_b32_e32 v52, v2
	v_mov_b32_e32 v53, v2
	v_mov_b32_e32 v54, v2
	v_mov_b32_e32 v55, v2
	v_mov_b32_e32 v56, v2
	v_mov_b32_e32 v57, v2
	v_mov_b32_e32 v58, v2
	v_mov_b32_e32 v59, v2
	v_mov_b32_e32 v83, v2
	v_mov_b32_e32 v84, v2
	v_mov_b32_e32 v85, v2
	v_mov_b32_e32 v86, v2
	v_mov_b32_e32 v87, v2
	v_mov_b32_e32 v88, v2
	v_mov_b32_e32 v89, v2
	v_mov_b32_e32 v90, v2
	v_mov_b32_e32 v91, v2
	v_mov_b32_e32 v92, v2
	v_mov_b32_e32 v93, v2
	v_mov_b32_e32 v94, v2
	v_mov_b32_e32 v95, v2
	v_mov_b32_e32 v96, v2
	v_mov_b32_e32 v97, v2
	v_mov_b32_e32 v98, v2
	v_mov_b32_e32 v99, v2
	v_mov_b32_e32 v100, v2
	v_mov_b32_e32 v101, v2
	v_mov_b32_e32 v102, v2
	v_mov_b32_e32 v103, v2
	v_mov_b32_e32 v104, v2
	v_mov_b32_e32 v105, v2
	v_mov_b32_e32 v106, v2
	v_mov_b32_e32 v107, v2
	v_mov_b32_e32 v108, v2
	v_mov_b32_e32 v109, v2
	v_mov_b32_e32 v110, v2
	v_mov_b32_e32 v111, v2
	v_mov_b32_e32 v112, v2
	v_mov_b32_e32 v113, v2
	v_mov_b32_e32 v114, v2
	v_mov_b32_e32 v115, v2
	v_mov_b32_e32 v116, v2
	v_mov_b32_e32 v117, v2
	v_mov_b32_e32 v118, v2
	v_mov_b32_e32 v119, v2
	v_mov_b32_e32 v120, v2
	v_mov_b32_e32 v121, v2
	v_mov_b32_e32 v122, v2
	v_mov_b32_e32 v123, v2
	v_mov_b32_e32 v124, v2
	v_mov_b32_e32 v125, v2
	v_mov_b32_e32 v126, v2
	v_mov_b32_e32 v127, v2
	v_mov_b32_e32 v128, v2
	v_mov_b32_e32 v129, v2
	s_waitcnt lgkmcnt(0)
	s_barrier
	s_movk_i32 s97, 0x70
	v_readfirstlane_b32 s98, v136
	v_readfirstlane_b32 s99, v137
	v_subrev_u32_e32 v248, s98, v136
	v_bfi_b32 v248, s97, v146, v248
	v_add_u32_e32 v140, s16, v248
	v_add_u32_e32 v152, s17, v248
	v_add_u32_e32 v156, s18, v248
	v_add_u32_e32 v160, s19, v248
	s_add_u32 s98, s98, s8
	s_addc_u32 s99, s99, s9
	s_add_u32 s98, s98, 0x80
	s_addc_u32 s99, s99, 0
	v_readfirstlane_b32 s100, v138
	v_readfirstlane_b32 s101, v139
	v_subrev_u32_e32 v250, s100, v138
	v_bfi_b32 v250, s97, v146, v250
	v_add_u32_e32 v164, s20, v250
	v_add_u32_e32 v168, s21, v250
	v_add_u32_e32 v172, s22, v250
	v_add_u32_e32 v176, s23, v250
	s_add_u32 s100, s100, s8
	s_addc_u32 s101, s101, s9
	s_add_u32 s100, s100, 0x80
	s_addc_u32 s101, s101, 0
	v_readfirstlane_b32 s96, v146
	s_and_b32 s96, s96, 0xfc00
	s_add_u32 m0, s96, 0x8000
	s_nop 0
	global_load_lds_dwordx4 v140, s[98:99]
	s_add_u32 m0, m0, 0x2000
	s_nop 0
	global_load_lds_dwordx4 v152, s[98:99]
	s_add_u32 m0, m0, 0x2000
	s_nop 0
	global_load_lds_dwordx4 v156, s[98:99]
	s_add_u32 m0, m0, 0x2000
	s_nop 0
	global_load_lds_dwordx4 v160, s[98:99]
	s_add_u32 m0, m0, 0xa000
	s_nop 0
	global_load_lds_dwordx4 v164, s[100:101]
	s_add_u32 m0, m0, 0x2000
	s_nop 0
	global_load_lds_dwordx4 v168, s[100:101]
	s_add_u32 m0, m0, 0x2000
	s_nop 0
	global_load_lds_dwordx4 v172, s[100:101]
	s_add_u32 m0, m0, 0x2000
	s_nop 0
	global_load_lds_dwordx4 v176, s[100:101]
	ds_read_b128 v[180:183], v148
	ds_read_b128 v[184:187], v148 offset:2048
	ds_read_b128 v[188:191], v148 offset:4096
	ds_read_b128 v[192:195], v148 offset:6144
	ds_read_b128 v[212:215], v149
	ds_read_b128 v[218:221], v149 offset:2048
	ds_read_b128 v[224:227], v149 offset:4096
	ds_read_b128 v[228:231], v149 offset:6144
